# attention loops: s_setprio 2 around every MFMA burst (QK^T and PV), back to 0 for the vector phase
# speedup vs baseline: 1.0112x; 1.0026x over previous
; DI float fexp2(float x) { return __builtin_amdgcn_exp2f(x); }
; DI void phase_attn(const Params& p, int hf, bool skipctx, char* smem, int& rot) {
;     ...
;     auto compute = [&](int buf, int half) {
;       const char* sk = smem + buf * STG + half * 64 * KROW; const char* sv = smem + buf * STG + KB_ + half * 128;
;       f32x16 st[2]; st[0] = zero16(); st[1] = zero16();
;       {
;         bf16x8 kf[2][6];
; #pragma unroll
;         for (int kb = 0; kb < 2; ++kb)
; #pragma unroll
;           for (int ks = 0; ks < 6; ++ks) kf[kb][ks] = *(const bf16x8*)(sk + (kb * 32 + r) * KROW + (ks * 16 + h * 8) * 2);
;         __builtin_amdgcn_sched_barrier(0);
; #pragma unroll
;         for (int ks = 0; ks < 6; ++ks)
; #pragma unroll
;           for (int kb = 0; kb < 2; ++kb) st[kb] = MFMA(kf[kb][ks], qf[ks], st[kb]);
;         __builtin_amdgcn_sched_barrier(0);
;       }
;       bf16x8 vf[2][2][2];
; #pragma unroll
;       for (int kb = 0; kb < 2; ++kb)
; #pragma unroll
;         for (int s2 = 0; s2 < 2; ++s2)
; #pragma unroll
;           for (int dvb = 0; dvb < 2; ++dvb) {
;             const char* vp = sv + (dvb * 32 + r) * VROW + (kb * 32 + 16 * s2 + 4 * h) * 2;
;             const s16x4 lo = *(const s16x4*)vp, hi = *(const s16x4*)(vp + 16);
;             vf[kb][s2][dvb] = __builtin_shufflevector(lo, hi, 0, 1, 2, 3, 4, 5, 6, 7);
;           }
;       float mx = st[0][0];
; #pragma unroll
;       for (int i = 0; i < 16; ++i) { mx = fmaxf(mx, st[0][i]); mx = fmaxf(mx, st[1][i]); }
;       if (__any(mx > m_run + 8.f)) {
;         mx = fmaxf(mx, __shfl_xor(mx, 32));
;         const float m_new = fmaxf(m_run, mx);
;         const float alpha = fexp2(m_run - m_new);
;         m_run = m_new;
;         l_run *= alpha;
; #pragma unroll
;         for (int i = 0; i < 16; ++i) { o[0][i] *= alpha; o[1][i] *= alpha; }
;       }
;       float ps = 0.f;
; #pragma unroll
;       for (int kb = 0; kb < 2; ++kb)
; #pragma unroll
;         for (int i = 0; i < 16; ++i) { const float e = fexp2(st[kb][i] - m_run); st[kb][i] = e; ps += e; }
;       l_run += ps;
; #pragma unroll
;       for (int kb = 0; kb < 2; ++kb)
; #pragma unroll
;         for (int s2 = 0; s2 < 2; ++s2) {
;           const bf16x8 pb = pack8(st[kb][8 * s2 + 0], st[kb][8 * s2 + 1], st[kb][8 * s2 + 2], st[kb][8 * s2 + 3], st[kb][8 * s2 + 4], st[kb][8 * s2 + 5], st[kb][8 * s2 + 6], st[kb][8 * s2 + 7]);
; #pragma unroll
.LBB0_797:
	s_cmp_eq_u32 s101, 0
	s_cbranch_scc1 .Lsc0_fb0e
	s_waitcnt lgkmcnt(11)
	s_setprio 2
	v_mfma_f32_32x32x16_bf16 v[48:63], v[32:35], v[64:67], v[176:191]
	s_waitcnt lgkmcnt(5)
	v_mfma_f32_32x32x16_bf16 v[32:47], v[36:39], v[64:67], v[176:191]
	v_mfma_f32_32x32x16_bf16 v[48:63], v[128:131], v[68:71], v[48:63]
	s_waitcnt lgkmcnt(4)
	v_mfma_f32_32x32x16_bf16 v[32:47], v[148:151], v[68:71], v[32:47]
	v_mfma_f32_32x32x16_bf16 v[48:63], v[132:135], v[72:75], v[48:63]
	s_waitcnt lgkmcnt(3)
	v_mfma_f32_32x32x16_bf16 v[32:47], v[152:155], v[72:75], v[32:47]
	v_mfma_f32_32x32x16_bf16 v[48:63], v[136:139], v[88:91], v[48:63]
	s_waitcnt lgkmcnt(2)
	v_mfma_f32_32x32x16_bf16 v[32:47], v[156:159], v[88:91], v[32:47]
	v_mfma_f32_32x32x16_bf16 v[48:63], v[140:143], v[96:99], v[48:63]
	s_waitcnt lgkmcnt(1)
	v_mfma_f32_32x32x16_bf16 v[32:47], v[214:217], v[96:99], v[32:47]
	v_mfma_f32_32x32x16_bf16 v[48:63], v[144:147], v[100:103], v[48:63]
	s_waitcnt lgkmcnt(0)
	v_mfma_f32_32x32x16_bf16 v[32:47], v[234:237], v[100:103], v[32:47]
	s_setprio 0
	s_nop 3
	ds_read_b128 v[156:159], v211 offset:0
	ds_read_b128 v[148:151], v211 offset:32
	ds_read_b128 v[152:155], v211 offset:8704
	ds_read_b128 v[144:147], v211 offset:8736
	ds_read_b128 v[140:143], v211 offset:64
	ds_read_b128 v[136:139], v211 offset:8768
	ds_read_b128 v[132:135], v211 offset:96
	ds_read_b128 v[128:131], v211 offset:8800
	v_exp_f32_e32 v48, v48
	v_exp_f32_e32 v49, v49
	v_exp_f32_e32 v50, v50
	v_exp_f32_e32 v51, v51
	v_exp_f32_e32 v52, v52
	v_exp_f32_e32 v53, v53
	v_exp_f32_e32 v54, v54
	v_exp_f32_e32 v55, v55
	v_exp_f32_e32 v56, v56
	v_exp_f32_e32 v57, v57
	v_exp_f32_e32 v58, v58
	v_exp_f32_e32 v59, v59
	v_exp_f32_e32 v60, v60
	v_exp_f32_e32 v61, v61
	v_exp_f32_e32 v62, v62
	v_exp_f32_e32 v63, v63
	v_exp_f32_e32 v32, v32
	v_exp_f32_e32 v33, v33
	v_exp_f32_e32 v34, v34
	v_exp_f32_e32 v35, v35
	v_exp_f32_e32 v36, v36
	v_exp_f32_e32 v37, v37
	v_exp_f32_e32 v38, v38
	v_exp_f32_e32 v39, v39
	v_exp_f32_e32 v40, v40
	v_exp_f32_e32 v41, v41
	v_exp_f32_e32 v42, v42
	v_exp_f32_e32 v43, v43
	v_exp_f32_e32 v44, v44
	v_exp_f32_e32 v45, v45
	v_exp_f32_e32 v46, v46
	v_exp_f32_e32 v47, v47
	v_add_f32_e32 v195, v48, v49
	v_add_f32_e32 v195, v195, v50
	v_add_f32_e32 v195, v195, v51
	v_add_f32_e32 v195, v195, v52
	v_add_f32_e32 v195, v195, v53
	v_add_f32_e32 v195, v195, v54
	v_add_f32_e32 v195, v195, v55
	v_add_f32_e32 v195, v195, v56
	v_add_f32_e32 v195, v195, v57
	v_add_f32_e32 v195, v195, v58
	v_add_f32_e32 v195, v195, v59
	v_add_f32_e32 v195, v195, v60
	v_add_f32_e32 v195, v195, v61
	v_add_f32_e32 v195, v195, v62
	v_add_f32_e32 v195, v195, v63
	v_add_f32_e32 v195, v195, v32
	v_add_f32_e32 v195, v195, v33
	v_add_f32_e32 v195, v195, v34
	v_add_f32_e32 v195, v195, v35
	v_add_f32_e32 v195, v195, v36
	v_add_f32_e32 v195, v195, v37
	v_add_f32_e32 v195, v195, v38
	v_add_f32_e32 v195, v195, v39
	v_add_f32_e32 v195, v195, v40
	v_add_f32_e32 v195, v195, v41
	v_add_f32_e32 v195, v195, v42
	v_add_f32_e32 v195, v195, v43
	v_add_f32_e32 v195, v195, v44
	v_add_f32_e32 v195, v195, v45
	v_add_f32_e32 v195, v195, v46
	v_add_f32_e32 v195, v195, v47
	v_cmp_nle_f32_e32 vcc, v195, v167
	s_cbranch_vccnz .Lsc0_fb0
	v_add_f32_e32 v213, v213, v195
	v_cvt_pk_bf16_f32 v48, v48, v49
	v_cvt_pk_bf16_f32 v49, v50, v51
	v_cvt_pk_bf16_f32 v50, v52, v53
	v_cvt_pk_bf16_f32 v51, v54, v55
	v_cvt_pk_bf16_f32 v52, v56, v57
	v_cvt_pk_bf16_f32 v53, v58, v59
	v_cvt_pk_bf16_f32 v54, v60, v61
	v_cvt_pk_bf16_f32 v55, v62, v63
	v_cvt_pk_bf16_f32 v56, v32, v33
	v_cvt_pk_bf16_f32 v57, v34, v35
	v_cvt_pk_bf16_f32 v58, v36, v37
	v_cvt_pk_bf16_f32 v59, v38, v39
	v_cvt_pk_bf16_f32 v60, v40, v41
	v_cvt_pk_bf16_f32 v61, v42, v43
	v_cvt_pk_bf16_f32 v62, v44, v45
	v_cvt_pk_bf16_f32 v63, v46, v47
	s_waitcnt lgkmcnt(7)
	s_setprio 2
	v_mfma_f32_32x32x16_bf16 v[16:31], v[156:159], v[48:51], v[16:31]
	s_waitcnt lgkmcnt(5)
	v_mfma_f32_32x32x16_bf16 v[0:15], v[152:155], v[48:51], v[0:15]
	s_nop 0
	v_mfma_f32_32x32x16_bf16 v[16:31], v[148:151], v[52:55], v[16:31]
	s_waitcnt lgkmcnt(4)
	v_mfma_f32_32x32x16_bf16 v[0:15], v[144:147], v[52:55], v[0:15]
	s_waitcnt lgkmcnt(3)
	v_mfma_f32_32x32x16_bf16 v[16:31], v[140:143], v[56:59], v[16:31]
	s_waitcnt lgkmcnt(2)
	v_mfma_f32_32x32x16_bf16 v[0:15], v[136:139], v[56:59], v[0:15]
	s_waitcnt lgkmcnt(1)
	s_nop 0
	v_mfma_f32_32x32x16_bf16 v[16:31], v[132:135], v[60:63], v[16:31]
	ds_read_b128 v[36:39], v210 offset:13312
	ds_read_b128 v[132:135], v210 offset:13344
	ds_read_b128 v[136:139], v210 offset:13376
	ds_read_b128 v[140:143], v210 offset:13408
	ds_read_b128 v[144:147], v210 offset:13440
	ds_read_b128 v[148:151], v210 offset:13472
	ds_read_b128 v[40:43], v210 offset:19968
	ds_read_b128 v[152:155], v210 offset:20000
	ds_read_b128 v[156:159], v210 offset:20032
	ds_read_b128 v[234:237], v210 offset:20064
	ds_read_b128 v[238:241], v210 offset:20096
	ds_read_b128 v[242:245], v210 offset:20128
	s_waitcnt lgkmcnt(12)
	v_mfma_f32_32x32x16_bf16 v[0:15], v[128:131], v[60:63], v[0:15]
	s_setprio 0
; DI float fexp2(float x) { return __builtin_amdgcn_exp2f(x); }
; DI void phase_attn(const Params& p, int hf, bool skipctx, char* smem, int& rot) {
;     ...
;           for (int kb = 0; kb < 2; ++kb) st[kb] = MFMA(kf[kb][ks], qf[ks], st[kb]);
;         __builtin_amdgcn_sched_barrier(0);
;       }
;       bf16x8 vf[2][2][2];
; #pragma unroll
;       for (int kb = 0; kb < 2; ++kb)
; #pragma unroll
;         for (int s2 = 0; s2 < 2; ++s2)
; #pragma unroll
;           for (int dvb = 0; dvb < 2; ++dvb) {
;             const char* vp = sv + (dvb * 32 + r) * VROW + (kb * 32 + 16 * s2 + 4 * h) * 2;
;             const s16x4 lo = *(const s16x4*)vp, hi = *(const s16x4*)(vp + 16);
;             vf[kb][s2][dvb] = __builtin_shufflevector(lo, hi, 0, 1, 2, 3, 4, 5, 6, 7);
;           }
;       float mx = st[0][0];
; #pragma unroll
;       for (int i = 0; i < 16; ++i) { mx = fmaxf(mx, st[0][i]); mx = fmaxf(mx, st[1][i]); }
;       if (__any(mx > m_run + 8.f)) {
;         mx = fmaxf(mx, __shfl_xor(mx, 32));
;         const float m_new = fmaxf(m_run, mx);
;         const float alpha = fexp2(m_run - m_new);
;         m_run = m_new;
;         l_run *= alpha;
; #pragma unroll
;         for (int i = 0; i < 16; ++i) { o[0][i] *= alpha; o[1][i] *= alpha; }
;       }
;       float ps = 0.f;
; #pragma unroll
;       for (int kb = 0; kb < 2; ++kb)
; #pragma unroll
;         for (int i = 0; i < 16; ++i) { const float e = fexp2(st[kb][i] - m_run); st[kb][i] = e; ps += e; }
;       l_run += ps;
; #pragma unroll
;       for (int kb = 0; kb < 2; ++kb)
; #pragma unroll
;         for (int s2 = 0; s2 < 2; ++s2) {
;           const bf16x8 pb = pack8(st[kb][8 * s2 + 0], st[kb][8 * s2 + 1], st[kb][8 * s2 + 2], st[kb][8 * s2 + 3], st[kb][8 * s2 + 4], st[kb][8 * s2 + 5], st[kb][8 * s2 + 6], st[kb][8 * s2 + 7]);
; #pragma unroll
;           for (int dvb = 0; dvb < 2; ++dvb) o[dvb] = MFMA(vf[kb][s2][dvb], pb, o[dvb]);
;         }
;     };
;     __syncthreads();
;     ATT_LOAD(ak0, ak1, ak2, av0, av1, 0);
;     ATT_LOAD(bk0, bk1, bk2, bv0, bv1, 1);
;     ATT_WRITE(ak0, ak1, ak2, av0, av1, 0);
;     __syncthreads();
;     for (int kt = 0; kt < nkt; kt += 2) {
;       if (kt + 2 < nkt) ATT_LOAD(ak0, ak1, ak2, av0, av1, kt + 2);
;       compute(0, 0); compute(0, 1);
;       ATT_WRITE(bk0, bk1, bk2, bv0, bv1, 1);
;       __syncthreads();
;       if (kt + 3 < nkt) ATT_LOAD(bk0, bk1, bk2, bv0, bv1, kt + 3);
.Lsc0_mj0:
	s_waitcnt lgkmcnt(11)
	s_setprio 2
	v_mfma_f32_32x32x16_bf16 v[48:63], v[36:39], v[64:67], v[176:191]
	s_waitcnt lgkmcnt(5)
	v_mfma_f32_32x32x16_bf16 v[32:47], v[40:43], v[64:67], v[176:191]
	v_mfma_f32_32x32x16_bf16 v[48:63], v[132:135], v[68:71], v[48:63]
	s_waitcnt lgkmcnt(4)
	v_mfma_f32_32x32x16_bf16 v[32:47], v[152:155], v[68:71], v[32:47]
	v_mfma_f32_32x32x16_bf16 v[48:63], v[136:139], v[72:75], v[48:63]
	s_waitcnt lgkmcnt(3)
	v_mfma_f32_32x32x16_bf16 v[32:47], v[156:159], v[72:75], v[32:47]
	v_mfma_f32_32x32x16_bf16 v[48:63], v[140:143], v[88:91], v[48:63]
	s_waitcnt lgkmcnt(2)
	v_mfma_f32_32x32x16_bf16 v[32:47], v[234:237], v[88:91], v[32:47]
	v_mfma_f32_32x32x16_bf16 v[48:63], v[144:147], v[96:99], v[48:63]
	s_waitcnt lgkmcnt(1)
	v_mfma_f32_32x32x16_bf16 v[32:47], v[238:241], v[96:99], v[32:47]
	v_mfma_f32_32x32x16_bf16 v[48:63], v[148:151], v[100:103], v[48:63]
	s_waitcnt lgkmcnt(0)
	v_mfma_f32_32x32x16_bf16 v[32:47], v[242:245], v[100:103], v[32:47]
	s_setprio 0
	s_nop 3
	ds_read_b128 v[156:159], v211 offset:128
	ds_read_b128 v[148:151], v211 offset:160
	ds_read_b128 v[152:155], v211 offset:8832
	ds_read_b128 v[144:147], v211 offset:8864
	ds_read_b128 v[140:143], v211 offset:192
	ds_read_b128 v[136:139], v211 offset:8896
	ds_read_b128 v[128:131], v211 offset:224
	ds_read_b128 v[132:135], v211 offset:8928
	v_exp_f32_e32 v48, v48
	v_exp_f32_e32 v49, v49
	v_exp_f32_e32 v50, v50
	v_exp_f32_e32 v51, v51
	v_exp_f32_e32 v52, v52
	v_exp_f32_e32 v53, v53
	v_exp_f32_e32 v54, v54
	v_exp_f32_e32 v55, v55
	v_exp_f32_e32 v56, v56
	v_exp_f32_e32 v57, v57
	v_exp_f32_e32 v58, v58
	v_exp_f32_e32 v59, v59
	v_exp_f32_e32 v60, v60
	v_exp_f32_e32 v61, v61
	v_exp_f32_e32 v62, v62
	v_exp_f32_e32 v63, v63
	v_exp_f32_e32 v32, v32
	v_exp_f32_e32 v33, v33
	v_exp_f32_e32 v34, v34
	v_exp_f32_e32 v35, v35
	v_exp_f32_e32 v36, v36
	v_exp_f32_e32 v37, v37
	v_exp_f32_e32 v38, v38
	v_exp_f32_e32 v39, v39
	v_exp_f32_e32 v40, v40
	v_exp_f32_e32 v41, v41
	v_exp_f32_e32 v42, v42
	v_exp_f32_e32 v43, v43
	v_exp_f32_e32 v44, v44
	v_exp_f32_e32 v45, v45
	v_exp_f32_e32 v46, v46
	v_exp_f32_e32 v47, v47
	v_add_f32_e32 v195, v48, v49
	v_add_f32_e32 v195, v195, v50
	v_add_f32_e32 v195, v195, v51
	v_add_f32_e32 v195, v195, v52
	v_add_f32_e32 v195, v195, v53
	v_add_f32_e32 v195, v195, v54
	v_add_f32_e32 v195, v195, v55
	v_add_f32_e32 v195, v195, v56
	v_add_f32_e32 v195, v195, v57
	v_add_f32_e32 v195, v195, v58
	v_add_f32_e32 v195, v195, v59
	v_add_f32_e32 v195, v195, v60
	v_add_f32_e32 v195, v195, v61
	v_add_f32_e32 v195, v195, v62
	v_add_f32_e32 v195, v195, v63
	v_add_f32_e32 v195, v195, v32
	v_add_f32_e32 v195, v195, v33
	v_add_f32_e32 v195, v195, v34
	v_add_f32_e32 v195, v195, v35
	v_add_f32_e32 v195, v195, v36
	v_add_f32_e32 v195, v195, v37
	v_add_f32_e32 v195, v195, v38
	v_add_f32_e32 v195, v195, v39
	v_add_f32_e32 v195, v195, v40
	v_add_f32_e32 v195, v195, v41
	v_add_f32_e32 v195, v195, v42
	v_add_f32_e32 v195, v195, v43
	v_add_f32_e32 v195, v195, v44
	v_add_f32_e32 v195, v195, v45
	v_add_f32_e32 v195, v195, v46
	v_add_f32_e32 v195, v195, v47
	v_cmp_nle_f32_e32 vcc, v195, v167
	s_cbranch_vccnz .Lsc0_fb1
	v_add_f32_e32 v213, v213, v195
	v_cvt_pk_bf16_f32 v48, v48, v49
	v_cvt_pk_bf16_f32 v49, v50, v51
	v_cvt_pk_bf16_f32 v50, v52, v53
	v_cvt_pk_bf16_f32 v51, v54, v55
	v_cvt_pk_bf16_f32 v52, v56, v57
	v_cvt_pk_bf16_f32 v53, v58, v59
	v_cvt_pk_bf16_f32 v54, v60, v61
	v_cvt_pk_bf16_f32 v55, v62, v63
	v_cvt_pk_bf16_f32 v56, v32, v33
	v_cvt_pk_bf16_f32 v57, v34, v35
	v_cvt_pk_bf16_f32 v58, v36, v37
	v_cvt_pk_bf16_f32 v59, v38, v39
	v_cvt_pk_bf16_f32 v60, v40, v41
	v_cvt_pk_bf16_f32 v61, v42, v43
	v_cvt_pk_bf16_f32 v62, v44, v45
	v_cvt_pk_bf16_f32 v63, v46, v47
	s_waitcnt lgkmcnt(7)
	s_nop 0
	s_setprio 2
	v_mfma_f32_32x32x16_bf16 v[16:31], v[156:159], v[48:51], v[16:31]
	s_waitcnt lgkmcnt(5)
	v_mfma_f32_32x32x16_bf16 v[0:15], v[152:155], v[48:51], v[0:15]
	s_nop 1
	v_mfma_f32_32x32x16_bf16 v[16:31], v[148:151], v[52:55], v[16:31]
	s_waitcnt lgkmcnt(4)
	v_mfma_f32_32x32x16_bf16 v[0:15], v[144:147], v[52:55], v[0:15]
	s_waitcnt lgkmcnt(3)
	s_nop 0
	v_mfma_f32_32x32x16_bf16 v[16:31], v[140:143], v[56:59], v[16:31]
	s_waitcnt lgkmcnt(2)
	v_mfma_f32_32x32x16_bf16 v[0:15], v[136:139], v[56:59], v[0:15]
	s_setprio 0
	s_add_i32 s4, s4, 3
	s_cmp_ge_u32 s4, s13
	s_waitcnt lgkmcnt(1)
	s_setprio 2
	v_mfma_f32_32x32x16_bf16 v[16:31], v[128:131], v[60:63], v[16:31]
	s_setprio 0
	s_waitcnt vmcnt(1)
	ds_write_b128 v194, v[112:115] offset:44032
	ds_write_b128 v204, v[108:111] offset:44032
	ds_write_b128 v206, v[116:119] offset:44032
	ds_write_b64 v208, v[120:121] offset:44032
	ds_write_b64 v208, v[122:123] offset:44048
	s_waitcnt vmcnt(0)
	ds_write_b64 v208, v[124:125] offset:52736
	ds_write_b64 v208, v[126:127] offset:52752
	s_waitcnt lgkmcnt(0)
	s_barrier
	s_setprio 2
	v_mfma_f32_32x32x16_bf16 v[0:15], v[132:135], v[60:63], v[0:15]
	s_setprio 0
	s_cbranch_scc1 .LBB0_803
	v_add_u32_e32 v200, 0x6000, v174
	v_add_u32_e32 v201, 0x6000, v172
	v_add_u32_e32 v202, 0x6000, v170
	global_load_dwordx4 v[112:115], v200, s[94:95]
	global_load_dwordx4 v[108:111], v201, s[94:95]
	global_load_dwordx4 v[116:119], v202, s[94:95]
	global_load_dwordx4 v[120:123], v166, s[94:95]
	global_load_dwordx4 v[124:127], v168, s[94:95]

; DI float fexp2(float x) { return __builtin_amdgcn_exp2f(x); }
; DI void phase_attn(const Params& p, int hf, bool skipctx, char* smem, int& rot) {
;     ...
;     auto compute = [&](int buf, int half) {
;       const char* sk = smem + buf * STG + half * 64 * KROW; const char* sv = smem + buf * STG + KB_ + half * 128;
;       f32x16 st[2]; st[0] = zero16(); st[1] = zero16();
;       {
;         bf16x8 kf[2][6];
; #pragma unroll
;         for (int kb = 0; kb < 2; ++kb)
; #pragma unroll
;           for (int ks = 0; ks < 6; ++ks) kf[kb][ks] = *(const bf16x8*)(sk + (kb * 32 + r) * KROW + (ks * 16 + h * 8) * 2);
;         __builtin_amdgcn_sched_barrier(0);
; #pragma unroll
;         for (int ks = 0; ks < 6; ++ks)
; #pragma unroll
;           for (int kb = 0; kb < 2; ++kb) st[kb] = MFMA(kf[kb][ks], qf[ks], st[kb]);
;         __builtin_amdgcn_sched_barrier(0);
;       }
;       bf16x8 vf[2][2][2];
; #pragma unroll
;       for (int kb = 0; kb < 2; ++kb)
; #pragma unroll
;         for (int s2 = 0; s2 < 2; ++s2)
; #pragma unroll
;           for (int dvb = 0; dvb < 2; ++dvb) {
;             const char* vp = sv + (dvb * 32 + r) * VROW + (kb * 32 + 16 * s2 + 4 * h) * 2;
;             const s16x4 lo = *(const s16x4*)vp, hi = *(const s16x4*)(vp + 16);
;             vf[kb][s2][dvb] = __builtin_shufflevector(lo, hi, 0, 1, 2, 3, 4, 5, 6, 7);
;           }
;       float mx = st[0][0];
; #pragma unroll
;       for (int i = 0; i < 16; ++i) { mx = fmaxf(mx, st[0][i]); mx = fmaxf(mx, st[1][i]); }
;       if (__any(mx > m_run + 8.f)) {
;         mx = fmaxf(mx, __shfl_xor(mx, 32));
;         const float m_new = fmaxf(m_run, mx);
;         const float alpha = fexp2(m_run - m_new);
;         m_run = m_new;
;         l_run *= alpha;
; #pragma unroll
;         for (int i = 0; i < 16; ++i) { o[0][i] *= alpha; o[1][i] *= alpha; }
;       }
;       float ps = 0.f;
; #pragma unroll
;       for (int kb = 0; kb < 2; ++kb)
; #pragma unroll
;         for (int i = 0; i < 16; ++i) { const float e = fexp2(st[kb][i] - m_run); st[kb][i] = e; ps += e; }
;       l_run += ps;
; #pragma unroll
;       for (int kb = 0; kb < 2; ++kb)
; #pragma unroll
;         for (int s2 = 0; s2 < 2; ++s2) {
;           const bf16x8 pb = pack8(st[kb][8 * s2 + 0], st[kb][8 * s2 + 1], st[kb][8 * s2 + 2], st[kb][8 * s2 + 3], st[kb][8 * s2 + 4], st[kb][8 * s2 + 5], st[kb][8 * s2 + 6], st[kb][8 * s2 + 7]);
; #pragma unroll
.Lsc0_mj1:
	s_waitcnt lgkmcnt(11)
	s_setprio 2
	v_mfma_f32_32x32x16_bf16 v[48:63], v[32:35], v[64:67], v[176:191]
	s_waitcnt lgkmcnt(5)
	v_mfma_f32_32x32x16_bf16 v[32:47], v[36:39], v[64:67], v[176:191]
	v_mfma_f32_32x32x16_bf16 v[48:63], v[128:131], v[68:71], v[48:63]
	s_waitcnt lgkmcnt(4)
	v_mfma_f32_32x32x16_bf16 v[32:47], v[148:151], v[68:71], v[32:47]
	v_mfma_f32_32x32x16_bf16 v[48:63], v[132:135], v[72:75], v[48:63]
	s_waitcnt lgkmcnt(3)
	v_mfma_f32_32x32x16_bf16 v[32:47], v[152:155], v[72:75], v[32:47]
	v_mfma_f32_32x32x16_bf16 v[48:63], v[136:139], v[88:91], v[48:63]
	s_waitcnt lgkmcnt(2)
	v_mfma_f32_32x32x16_bf16 v[32:47], v[156:159], v[88:91], v[32:47]
	v_mfma_f32_32x32x16_bf16 v[48:63], v[140:143], v[96:99], v[48:63]
	s_waitcnt lgkmcnt(1)
	v_mfma_f32_32x32x16_bf16 v[32:47], v[214:217], v[96:99], v[32:47]
	v_mfma_f32_32x32x16_bf16 v[48:63], v[144:147], v[100:103], v[48:63]
	s_waitcnt lgkmcnt(0)
	v_mfma_f32_32x32x16_bf16 v[32:47], v[234:237], v[100:103], v[32:47]
	s_setprio 0
	s_nop 3
	ds_read_b128 v[152:155], v211 offset:52736
	ds_read_b128 v[156:159], v211 offset:44032
	ds_read_b128 v[148:151], v211 offset:44064
	ds_read_b128 v[144:147], v211 offset:52768
	ds_read_b128 v[140:143], v211 offset:44096
	ds_read_b128 v[136:139], v211 offset:52800
	ds_read_b128 v[132:135], v211 offset:44128
	ds_read_b128 v[128:131], v211 offset:52832
	v_exp_f32_e32 v48, v48
	v_exp_f32_e32 v49, v49
	v_exp_f32_e32 v50, v50
	v_exp_f32_e32 v51, v51
	v_exp_f32_e32 v52, v52
	v_exp_f32_e32 v53, v53
	v_exp_f32_e32 v54, v54
	v_exp_f32_e32 v55, v55
	v_exp_f32_e32 v56, v56
	v_exp_f32_e32 v57, v57
	v_exp_f32_e32 v58, v58
	v_exp_f32_e32 v59, v59
	v_exp_f32_e32 v60, v60
	v_exp_f32_e32 v61, v61
	v_exp_f32_e32 v62, v62
	v_exp_f32_e32 v63, v63
	v_exp_f32_e32 v32, v32
	v_exp_f32_e32 v33, v33
	v_exp_f32_e32 v34, v34
	v_exp_f32_e32 v35, v35
	v_exp_f32_e32 v36, v36
	v_exp_f32_e32 v37, v37
	v_exp_f32_e32 v38, v38
	v_exp_f32_e32 v39, v39
	v_exp_f32_e32 v40, v40
	v_exp_f32_e32 v41, v41
	v_exp_f32_e32 v42, v42
	v_exp_f32_e32 v43, v43
	v_exp_f32_e32 v44, v44
	v_exp_f32_e32 v45, v45
	v_exp_f32_e32 v46, v46
	v_exp_f32_e32 v47, v47
	v_add_f32_e32 v195, v48, v49
	v_add_f32_e32 v195, v195, v50
	v_add_f32_e32 v195, v195, v51
	v_add_f32_e32 v195, v195, v52
	v_add_f32_e32 v195, v195, v53
	v_add_f32_e32 v195, v195, v54
	v_add_f32_e32 v195, v195, v55
	v_add_f32_e32 v195, v195, v56
	v_add_f32_e32 v195, v195, v57
	v_add_f32_e32 v195, v195, v58
	v_add_f32_e32 v195, v195, v59
	v_add_f32_e32 v195, v195, v60
	v_add_f32_e32 v195, v195, v61
	v_add_f32_e32 v195, v195, v62
	v_add_f32_e32 v195, v195, v63
	v_add_f32_e32 v195, v195, v32
	v_add_f32_e32 v195, v195, v33
	v_add_f32_e32 v195, v195, v34
	v_add_f32_e32 v195, v195, v35
	v_add_f32_e32 v195, v195, v36
	v_add_f32_e32 v195, v195, v37
	v_add_f32_e32 v195, v195, v38
	v_add_f32_e32 v195, v195, v39
	v_add_f32_e32 v195, v195, v40
	v_add_f32_e32 v195, v195, v41
	v_add_f32_e32 v195, v195, v42
	v_add_f32_e32 v195, v195, v43
	v_add_f32_e32 v195, v195, v44
	v_add_f32_e32 v195, v195, v45
	v_add_f32_e32 v195, v195, v46
	v_add_f32_e32 v195, v195, v47
	v_cmp_nle_f32_e32 vcc, v195, v167
	s_cbranch_vccnz .Lsc0_fb2
	v_add_f32_e32 v213, v213, v195
	v_cvt_pk_bf16_f32 v48, v48, v49
	v_cvt_pk_bf16_f32 v49, v50, v51
	v_cvt_pk_bf16_f32 v50, v52, v53
	v_cvt_pk_bf16_f32 v51, v54, v55
	v_cvt_pk_bf16_f32 v52, v56, v57
	v_cvt_pk_bf16_f32 v53, v58, v59
	v_cvt_pk_bf16_f32 v54, v60, v61
	v_cvt_pk_bf16_f32 v55, v62, v63
	v_cvt_pk_bf16_f32 v56, v32, v33
	v_cvt_pk_bf16_f32 v57, v34, v35
	v_cvt_pk_bf16_f32 v58, v36, v37
	v_cvt_pk_bf16_f32 v59, v38, v39
	v_cvt_pk_bf16_f32 v60, v40, v41
	v_cvt_pk_bf16_f32 v61, v42, v43
	v_cvt_pk_bf16_f32 v62, v44, v45
	v_cvt_pk_bf16_f32 v63, v46, v47
	s_waitcnt lgkmcnt(6)
	s_setprio 2
	v_mfma_f32_32x32x16_bf16 v[16:31], v[156:159], v[48:51], v[16:31]
	v_mfma_f32_32x32x16_bf16 v[0:15], v[152:155], v[48:51], v[0:15]
	s_waitcnt lgkmcnt(5)
	v_mfma_f32_32x32x16_bf16 v[16:31], v[148:151], v[52:55], v[16:31]
	s_waitcnt lgkmcnt(4)
	v_mfma_f32_32x32x16_bf16 v[0:15], v[144:147], v[52:55], v[0:15]
	s_waitcnt lgkmcnt(3)
	v_mfma_f32_32x32x16_bf16 v[16:31], v[140:143], v[56:59], v[16:31]
	s_waitcnt lgkmcnt(2)
	v_mfma_f32_32x32x16_bf16 v[0:15], v[136:139], v[56:59], v[0:15]
	s_waitcnt lgkmcnt(1)
	s_nop 0
	v_mfma_f32_32x32x16_bf16 v[16:31], v[132:135], v[60:63], v[16:31]
	ds_read_b128 v[36:39], v210 offset:57344
	ds_read_b128 v[132:135], v210 offset:57376
	ds_read_b128 v[136:139], v210 offset:57408
	ds_read_b128 v[140:143], v210 offset:57440
	ds_read_b128 v[144:147], v210 offset:57472
	ds_read_b128 v[148:151], v210 offset:57504
	ds_read_b128 v[40:43], v210 offset:64000
	ds_read_b128 v[152:155], v210 offset:64032
	ds_read_b128 v[156:159], v210 offset:64064
	ds_read_b128 v[216:219], v210 offset:64096
	ds_read_b128 v[234:237], v210 offset:64128
	ds_read_b128 v[238:241], v210 offset:64160
	s_waitcnt lgkmcnt(12)
	v_mfma_f32_32x32x16_bf16 v[0:15], v[128:131], v[60:63], v[0:15]
	s_setprio 0
; DI void phase_attn(const Params& p, int hf, bool skipctx, char* smem, int& rot) {
;     ...
;           for (int kb = 0; kb < 2; ++kb) st[kb] = MFMA(kf[kb][ks], qf[ks], st[kb]);
;         __builtin_amdgcn_sched_barrier(0);
;       }
;       bf16x8 vf[2][2][2];
; #pragma unroll
;       for (int kb = 0; kb < 2; ++kb)
; #pragma unroll
;         for (int s2 = 0; s2 < 2; ++s2)
; #pragma unroll
;           for (int dvb = 0; dvb < 2; ++dvb) {
;             const char* vp = sv + (dvb * 32 + r) * VROW + (kb * 32 + 16 * s2 + 4 * h) * 2;
;             const s16x4 lo = *(const s16x4*)vp, hi = *(const s16x4*)(vp + 16);
;             vf[kb][s2][dvb] = __builtin_shufflevector(lo, hi, 0, 1, 2, 3, 4, 5, 6, 7);
;           }
;       float mx = st[0][0];
; #pragma unroll
;       for (int i = 0; i < 16; ++i) { mx = fmaxf(mx, st[0][i]); mx = fmaxf(mx, st[1][i]); }
;       if (__any(mx > m_run + 8.f)) {
;         mx = fmaxf(mx, __shfl_xor(mx, 32));
;         const float m_new = fmaxf(m_run, mx);
;         const float alpha = fexp2(m_run - m_new);
;         m_run = m_new;
;         l_run *= alpha;
; #pragma unroll
;         for (int i = 0; i < 16; ++i) { o[0][i] *= alpha; o[1][i] *= alpha; }
;       }
;       float ps = 0.f;
; #pragma unroll
;       for (int kb = 0; kb < 2; ++kb)
; #pragma unroll
;         for (int i = 0; i < 16; ++i) { const float e = fexp2(st[kb][i] - m_run); st[kb][i] = e; ps += e; }
;       l_run += ps;
; #pragma unroll
;       for (int kb = 0; kb < 2; ++kb)
; #pragma unroll
;         for (int s2 = 0; s2 < 2; ++s2) {
;           const bf16x8 pb = pack8(st[kb][8 * s2 + 0], st[kb][8 * s2 + 1], st[kb][8 * s2 + 2], st[kb][8 * s2 + 3], st[kb][8 * s2 + 4], st[kb][8 * s2 + 5], st[kb][8 * s2 + 6], st[kb][8 * s2 + 7]);
; #pragma unroll
;           for (int dvb = 0; dvb < 2; ++dvb) o[dvb] = MFMA(vf[kb][s2][dvb], pb, o[dvb]);
;         }
;     };
;     __syncthreads();
;     ATT_LOAD(ak0, ak1, ak2, av0, av1, 0);
;     ATT_LOAD(bk0, bk1, bk2, bv0, bv1, 1);
;     ATT_WRITE(ak0, ak1, ak2, av0, av1, 0);
;     __syncthreads();
;     for (int kt = 0; kt < nkt; kt += 2) {
;       if (kt + 2 < nkt) ATT_LOAD(ak0, ak1, ak2, av0, av1, kt + 2);
;       compute(0, 0); compute(0, 1);
;       ATT_WRITE(bk0, bk1, bk2, bv0, bv1, 1);
;       __syncthreads();
;       if (kt + 3 < nkt) ATT_LOAD(bk0, bk1, bk2, bv0, bv1, kt + 3);
;       compute(1, 0); compute(1, 1);
.Lsc0_mj2:
	s_waitcnt lgkmcnt(11)
	s_setprio 2
	v_mfma_f32_32x32x16_bf16 v[48:63], v[36:39], v[64:67], v[176:191]
	s_waitcnt lgkmcnt(5)
	v_mfma_f32_32x32x16_bf16 v[32:47], v[40:43], v[64:67], v[176:191]
	v_mfma_f32_32x32x16_bf16 v[48:63], v[132:135], v[68:71], v[48:63]
	s_waitcnt lgkmcnt(4)
	v_mfma_f32_32x32x16_bf16 v[32:47], v[152:155], v[68:71], v[32:47]
	v_mfma_f32_32x32x16_bf16 v[48:63], v[136:139], v[72:75], v[48:63]
	s_waitcnt lgkmcnt(3)
	v_mfma_f32_32x32x16_bf16 v[32:47], v[156:159], v[72:75], v[32:47]
	v_mfma_f32_32x32x16_bf16 v[48:63], v[140:143], v[88:91], v[48:63]
	s_waitcnt lgkmcnt(2)
	v_mfma_f32_32x32x16_bf16 v[32:47], v[216:219], v[88:91], v[32:47]
	v_mfma_f32_32x32x16_bf16 v[48:63], v[144:147], v[96:99], v[48:63]
	s_waitcnt lgkmcnt(1)
	v_mfma_f32_32x32x16_bf16 v[32:47], v[234:237], v[96:99], v[32:47]
	v_mfma_f32_32x32x16_bf16 v[48:63], v[148:151], v[100:103], v[48:63]
	s_waitcnt lgkmcnt(0)
	v_mfma_f32_32x32x16_bf16 v[32:47], v[238:241], v[100:103], v[32:47]
	s_setprio 0
	s_nop 3
	ds_read_b128 v[152:155], v211 offset:52864
	ds_read_b128 v[156:159], v211 offset:44160
	ds_read_b128 v[148:151], v211 offset:44192
	ds_read_b128 v[144:147], v211 offset:52896
	ds_read_b128 v[140:143], v211 offset:44224
	ds_read_b128 v[136:139], v211 offset:52928
	ds_read_b128 v[132:135], v211 offset:44256
	ds_read_b128 v[128:131], v211 offset:52960
	v_exp_f32_e32 v48, v48
	v_exp_f32_e32 v49, v49
	v_exp_f32_e32 v50, v50
	v_exp_f32_e32 v51, v51
	v_exp_f32_e32 v52, v52
	v_exp_f32_e32 v53, v53
	v_exp_f32_e32 v54, v54
	v_exp_f32_e32 v55, v55
	v_exp_f32_e32 v56, v56
	v_exp_f32_e32 v57, v57
	v_exp_f32_e32 v58, v58
	v_exp_f32_e32 v59, v59
	v_exp_f32_e32 v60, v60
	v_exp_f32_e32 v61, v61
	v_exp_f32_e32 v62, v62
	v_exp_f32_e32 v63, v63
	v_exp_f32_e32 v32, v32
	v_exp_f32_e32 v33, v33
	v_exp_f32_e32 v34, v34
	v_exp_f32_e32 v35, v35
	v_exp_f32_e32 v36, v36
	v_exp_f32_e32 v37, v37
	v_exp_f32_e32 v38, v38
	v_exp_f32_e32 v39, v39
	v_exp_f32_e32 v40, v40
	v_exp_f32_e32 v41, v41
	v_exp_f32_e32 v42, v42
	v_exp_f32_e32 v43, v43
	v_exp_f32_e32 v44, v44
	v_exp_f32_e32 v45, v45
	v_exp_f32_e32 v46, v46
	v_exp_f32_e32 v47, v47
	v_add_f32_e32 v195, v48, v49
	v_add_f32_e32 v195, v195, v50
	v_add_f32_e32 v195, v195, v51
	v_add_f32_e32 v195, v195, v52
	v_add_f32_e32 v195, v195, v53
	v_add_f32_e32 v195, v195, v54
	v_add_f32_e32 v195, v195, v55
	v_add_f32_e32 v195, v195, v56
	v_add_f32_e32 v195, v195, v57
	v_add_f32_e32 v195, v195, v58
	v_add_f32_e32 v195, v195, v59
	v_add_f32_e32 v195, v195, v60
	v_add_f32_e32 v195, v195, v61
	v_add_f32_e32 v195, v195, v62
	v_add_f32_e32 v195, v195, v63
	v_add_f32_e32 v195, v195, v32
	v_add_f32_e32 v195, v195, v33
	v_add_f32_e32 v195, v195, v34
	v_add_f32_e32 v195, v195, v35
	v_add_f32_e32 v195, v195, v36
	v_add_f32_e32 v195, v195, v37
	v_add_f32_e32 v195, v195, v38
	v_add_f32_e32 v195, v195, v39
	v_add_f32_e32 v195, v195, v40
	v_add_f32_e32 v195, v195, v41
	v_add_f32_e32 v195, v195, v42
	v_add_f32_e32 v195, v195, v43
	v_add_f32_e32 v195, v195, v44
	v_add_f32_e32 v195, v195, v45
	v_add_f32_e32 v195, v195, v46
	v_add_f32_e32 v195, v195, v47
	v_cmp_nle_f32_e32 vcc, v195, v167
	s_cbranch_vccnz .Lsc0_fb3
	v_add_f32_e32 v213, v213, v195
	v_cvt_pk_bf16_f32 v48, v48, v49
	v_cvt_pk_bf16_f32 v49, v50, v51
	v_cvt_pk_bf16_f32 v50, v52, v53
	v_cvt_pk_bf16_f32 v51, v54, v55
	v_cvt_pk_bf16_f32 v52, v56, v57
	v_cvt_pk_bf16_f32 v53, v58, v59
	v_cvt_pk_bf16_f32 v54, v60, v61
	v_cvt_pk_bf16_f32 v55, v62, v63
	v_cvt_pk_bf16_f32 v56, v32, v33
	v_cvt_pk_bf16_f32 v57, v34, v35
	v_cvt_pk_bf16_f32 v58, v36, v37
	v_cvt_pk_bf16_f32 v59, v38, v39
	v_cvt_pk_bf16_f32 v60, v40, v41
	v_cvt_pk_bf16_f32 v61, v42, v43
	v_cvt_pk_bf16_f32 v62, v44, v45
	v_cvt_pk_bf16_f32 v63, v46, v47
	s_waitcnt lgkmcnt(6)
	s_nop 0
	s_setprio 2
	v_mfma_f32_32x32x16_bf16 v[16:31], v[156:159], v[48:51], v[16:31]
	v_mfma_f32_32x32x16_bf16 v[0:15], v[152:155], v[48:51], v[0:15]
	s_waitcnt lgkmcnt(5)
	s_nop 0
	v_mfma_f32_32x32x16_bf16 v[16:31], v[148:151], v[52:55], v[16:31]
	s_waitcnt lgkmcnt(4)
	v_mfma_f32_32x32x16_bf16 v[0:15], v[144:147], v[52:55], v[0:15]
	s_waitcnt lgkmcnt(3)
	s_nop 0
	v_mfma_f32_32x32x16_bf16 v[16:31], v[140:143], v[56:59], v[16:31]
	s_waitcnt lgkmcnt(2)
	v_mfma_f32_32x32x16_bf16 v[0:15], v[136:139], v[56:59], v[0:15]
	s_setprio 0
	s_andn2_b64 vcc, exec, s[36:37]
	s_waitcnt lgkmcnt(1)
	s_setprio 2
	v_mfma_f32_32x32x16_bf16 v[16:31], v[132:135], v[60:63], v[16:31]
	s_waitcnt lgkmcnt(0)
	v_mfma_f32_32x32x16_bf16 v[0:15], v[128:131], v[60:63], v[0:15]
	s_setprio 0
	s_cbranch_vccnz .LBB0_809
	ds_write_b128 v194, v[76:79]
	ds_write_b128 v204, v[80:83]
	ds_write_b128 v206, v[84:87]
	ds_write_b64 v208, v[92:93] offset:0
	ds_write_b64 v208, v[94:95] offset:16
	ds_write_b64 v208, v[104:105] offset:8704
	ds_write_b64 v208, v[106:107] offset:8720

; DI float fexp2(float x) { return __builtin_amdgcn_exp2f(x); }
; DI void phase_attn(const Params& p, int hf, bool skipctx, char* smem, int& rot) {
;     ...
;       float mx = st[0][0];
; #pragma unroll
;       for (int i = 0; i < 16; ++i) { mx = fmaxf(mx, st[0][i]); mx = fmaxf(mx, st[1][i]); }
;       if (__any(mx > m_run + 8.f)) {
;         mx = fmaxf(mx, __shfl_xor(mx, 32));
;         const float m_new = fmaxf(m_run, mx);
;         const float alpha = fexp2(m_run - m_new);
;         m_run = m_new;
;         l_run *= alpha;
; #pragma unroll
;         for (int i = 0; i < 16; ++i) { o[0][i] *= alpha; o[1][i] *= alpha; }
;       }
.Lsc0_fb0e:
	s_waitcnt lgkmcnt(11)
	s_setprio 2
	v_mfma_f32_32x32x16_bf16 v[48:63], v[32:35], v[64:67], v[176:191]
	s_waitcnt lgkmcnt(5)
	v_mfma_f32_32x32x16_bf16 v[32:47], v[36:39], v[64:67], v[176:191]
	v_mfma_f32_32x32x16_bf16 v[48:63], v[128:131], v[68:71], v[48:63]
	s_waitcnt lgkmcnt(4)
	v_mfma_f32_32x32x16_bf16 v[32:47], v[148:151], v[68:71], v[32:47]
	v_mfma_f32_32x32x16_bf16 v[48:63], v[132:135], v[72:75], v[48:63]
	s_waitcnt lgkmcnt(3)
	v_mfma_f32_32x32x16_bf16 v[32:47], v[152:155], v[72:75], v[32:47]
	v_mfma_f32_32x32x16_bf16 v[48:63], v[136:139], v[88:91], v[48:63]
	s_waitcnt lgkmcnt(2)
	v_mfma_f32_32x32x16_bf16 v[32:47], v[156:159], v[88:91], v[32:47]
	v_mfma_f32_32x32x16_bf16 v[48:63], v[140:143], v[96:99], v[48:63]
	s_waitcnt lgkmcnt(1)
	v_mfma_f32_32x32x16_bf16 v[32:47], v[214:217], v[96:99], v[32:47]
	v_mfma_f32_32x32x16_bf16 v[48:63], v[144:147], v[100:103], v[48:63]
	s_waitcnt lgkmcnt(0)
	v_mfma_f32_32x32x16_bf16 v[32:47], v[234:237], v[100:103], v[32:47]
	s_setprio 0
	s_nop 3
	ds_read_b128 v[156:159], v211 offset:0
	ds_read_b128 v[148:151], v211 offset:32
	ds_read_b128 v[152:155], v211 offset:8704
	ds_read_b128 v[144:147], v211 offset:8736
	ds_read_b128 v[140:143], v211 offset:64
	ds_read_b128 v[136:139], v211 offset:8768
	ds_read_b128 v[132:135], v211 offset:96
	ds_read_b128 v[128:131], v211 offset:8800
	v_max3_f32 v195, v32, v48, v49
	v_max_f32_e32 v195, v195, v33
	v_max3_f32 v195, v195, v50, v34
	v_max3_f32 v195, v195, v51, v35
	v_max3_f32 v195, v195, v52, v36
	v_max3_f32 v195, v195, v53, v37
	v_max3_f32 v195, v195, v54, v38
	v_max3_f32 v195, v195, v55, v39
	v_max3_f32 v195, v195, v56, v40
	v_max3_f32 v195, v195, v57, v41
	v_max3_f32 v195, v195, v58, v42
	v_max3_f32 v195, v195, v59, v43
	v_max3_f32 v195, v195, v60, v44
	v_max3_f32 v195, v195, v61, v45
	v_max3_f32 v195, v195, v62, v46
	v_max3_f32 v217, v195, v63, v47
	v_cmp_gt_f32_e32 vcc, v217, v220
	s_cbranch_vccz .Lsc0_c0_LBB0_799
	v_sub_f32_e32 v217, v217, v176
	v_cmp_lt_i32_e32 vcc, v224, v207
	s_nop 1
	v_cndmask_b32_e32 v195, v205, v224, vcc
	v_lshlrev_b32_e32 v195, 2, v195
	ds_bpermute_b32 v195, v195, v217
	s_waitcnt lgkmcnt(0)
	v_max3_f32 v195, v212, v217, v195
	v_sub_f32_e32 v200, v212, v195
	v_exp_f32_e32 v200, v200
	v_mov_b32_e32 v212, v195
	v_mul_f32_e32 v213, v213, v200
	v_pk_mul_f32 v[30:31], v[30:31], v[200:201] op_sel_hi:[1,0]
	v_pk_mul_f32 v[28:29], v[28:29], v[200:201] op_sel_hi:[1,0]
	v_pk_mul_f32 v[26:27], v[26:27], v[200:201] op_sel_hi:[1,0]
	v_pk_mul_f32 v[24:25], v[24:25], v[200:201] op_sel_hi:[1,0]
	v_pk_mul_f32 v[22:23], v[22:23], v[200:201] op_sel_hi:[1,0]
	v_pk_mul_f32 v[20:21], v[20:21], v[200:201] op_sel_hi:[1,0]
	v_pk_mul_f32 v[18:19], v[18:19], v[200:201] op_sel_hi:[1,0]
	v_pk_mul_f32 v[16:17], v[16:17], v[200:201] op_sel_hi:[1,0]
	v_pk_mul_f32 v[14:15], v[14:15], v[200:201] op_sel_hi:[1,0]
	v_pk_mul_f32 v[12:13], v[12:13], v[200:201] op_sel_hi:[1,0]
	v_pk_mul_f32 v[10:11], v[10:11], v[200:201] op_sel_hi:[1,0]
	v_pk_mul_f32 v[8:9], v[8:9], v[200:201] op_sel_hi:[1,0]
	v_pk_mul_f32 v[6:7], v[6:7], v[200:201] op_sel_hi:[1,0]
	v_pk_mul_f32 v[4:5], v[4:5], v[200:201] op_sel_hi:[1,0]
	v_pk_mul_f32 v[2:3], v[2:3], v[200:201] op_sel_hi:[1,0]
	v_pk_mul_f32 v[0:1], v[0:1], v[200:201] op_sel_hi:[1,0]
	v_add_f32_e32 v202, v195, v176
	v_sub_f32_e32 v32, v32, v202
	v_sub_f32_e32 v33, v33, v202
	v_sub_f32_e32 v34, v34, v202
	v_sub_f32_e32 v35, v35, v202
	v_sub_f32_e32 v36, v36, v202
	v_sub_f32_e32 v37, v37, v202
	v_sub_f32_e32 v38, v38, v202
	v_sub_f32_e32 v39, v39, v202
	v_sub_f32_e32 v40, v40, v202
	v_sub_f32_e32 v41, v41, v202
	v_sub_f32_e32 v42, v42, v202
	v_sub_f32_e32 v43, v43, v202
	v_sub_f32_e32 v44, v44, v202
	v_sub_f32_e32 v45, v45, v202
	v_sub_f32_e32 v46, v46, v202
	v_sub_f32_e32 v47, v47, v202
	v_sub_f32_e32 v48, v48, v202
	v_sub_f32_e32 v49, v49, v202
	v_sub_f32_e32 v50, v50, v202
	v_sub_f32_e32 v51, v51, v202
	v_sub_f32_e32 v52, v52, v202
	v_sub_f32_e32 v53, v53, v202
	v_sub_f32_e32 v54, v54, v202
	v_sub_f32_e32 v55, v55, v202
	v_sub_f32_e32 v56, v56, v202
	v_sub_f32_e32 v57, v57, v202
	v_sub_f32_e32 v58, v58, v202
	v_sub_f32_e32 v59, v59, v202
	v_sub_f32_e32 v60, v60, v202
	v_sub_f32_e32 v61, v61, v202
	v_sub_f32_e32 v62, v62, v202
	v_sub_f32_e32 v63, v63, v202
	v_sub_f32_e32 v176, 0, v195
	v_sub_f32_e32 v177, 0, v195
	v_sub_f32_e32 v178, 0, v195
	v_sub_f32_e32 v179, 0, v195
	v_sub_f32_e32 v180, 0, v195
	v_sub_f32_e32 v181, 0, v195
	v_sub_f32_e32 v182, 0, v195
	v_sub_f32_e32 v183, 0, v195
	v_sub_f32_e32 v184, 0, v195
	v_sub_f32_e32 v185, 0, v195
	v_sub_f32_e32 v186, 0, v195
	v_sub_f32_e32 v187, 0, v195
	v_sub_f32_e32 v188, 0, v195
	v_sub_f32_e32 v189, 0, v195
	v_sub_f32_e32 v190, 0, v195
	v_sub_f32_e32 v191, 0, v195
	v_mov_b32_e32 v220, 0x41000000
	v_mov_b32_e32 v167, 0x43800000
	s_mov_b32 s101, 1
; #define MFMA(a, b, c) __builtin_amdgcn_mfma_f32_32x32x16_bf16((a), (b), (c), 0, 0, 0)
; DI float fexp2(float x) { return __builtin_amdgcn_exp2f(x); }
; DI void phase_attn(const Params& p, int hf, bool skipctx, char* smem, int& rot) {
;     ...
;           for (int ks = 0; ks < 6; ++ks) kf[kb][ks] = *(const bf16x8*)(sk + (kb * 32 + r) * KROW + (ks * 16 + h * 8) * 2);
;         __builtin_amdgcn_sched_barrier(0);
; #pragma unroll
;         for (int ks = 0; ks < 6; ++ks)
; #pragma unroll
;           for (int kb = 0; kb < 2; ++kb) st[kb] = MFMA(kf[kb][ks], qf[ks], st[kb]);
;     ...
;       float mx = st[0][0];
; #pragma unroll
;       for (int i = 0; i < 16; ++i) { mx = fmaxf(mx, st[0][i]); mx = fmaxf(mx, st[1][i]); }
;       if (__any(mx > m_run + 8.f)) {
;         mx = fmaxf(mx, __shfl_xor(mx, 32));
;         const float m_new = fmaxf(m_run, mx);
;         const float alpha = fexp2(m_run - m_new);
;         m_run = m_new;
;         l_run *= alpha;
; #pragma unroll
;         for (int i = 0; i < 16; ++i) { o[0][i] *= alpha; o[1][i] *= alpha; }
;       }
;       float ps = 0.f;
; #pragma unroll
;       for (int kb = 0; kb < 2; ++kb)
; #pragma unroll
;         for (int i = 0; i < 16; ++i) { const float e = fexp2(st[kb][i] - m_run); st[kb][i] = e; ps += e; }
;       l_run += ps;
; #pragma unroll
;       for (int kb = 0; kb < 2; ++kb)
; #pragma unroll
;         for (int s2 = 0; s2 < 2; ++s2) {
;           const bf16x8 pb = pack8(st[kb][8 * s2 + 0], st[kb][8 * s2 + 1], st[kb][8 * s2 + 2], st[kb][8 * s2 + 3], st[kb][8 * s2 + 4], st[kb][8 * s2 + 5], st[kb][8 * s2 + 6], st[kb][8 * s2 + 7]);
; #pragma unroll
;           for (int dvb = 0; dvb < 2; ++dvb) o[dvb] = MFMA(vf[kb][s2][dvb], pb, o[dvb]);
;         }
.Lsc0_c0_LBB0_799:
	v_exp_f32_e32 v48, v48
	v_exp_f32_e32 v49, v49
	v_exp_f32_e32 v50, v50
	v_exp_f32_e32 v51, v51
	v_exp_f32_e32 v52, v52
	v_add_f32_e32 v195, v49, v48
	v_exp_f32_e32 v53, v53
	v_add_f32_e32 v195, v50, v195
	v_exp_f32_e32 v54, v54
	v_add_f32_e32 v195, v51, v195
	v_exp_f32_e32 v55, v55
	v_add_f32_e32 v195, v52, v195
	v_exp_f32_e32 v56, v56
	v_add_f32_e32 v195, v53, v195
	v_exp_f32_e32 v57, v57
	v_add_f32_e32 v195, v54, v195
	v_exp_f32_e32 v58, v58
	v_add_f32_e32 v195, v55, v195
	v_exp_f32_e32 v59, v59
	v_add_f32_e32 v195, v56, v195
	v_exp_f32_e32 v60, v60
	v_add_f32_e32 v195, v57, v195
	v_exp_f32_e32 v61, v61
	v_add_f32_e32 v195, v58, v195
	v_exp_f32_e32 v62, v62
	v_add_f32_e32 v195, v59, v195
	v_exp_f32_e32 v63, v63
	v_add_f32_e32 v195, v60, v195
	v_exp_f32_e32 v200, v32
	v_add_f32_e32 v195, v61, v195
	v_exp_f32_e32 v201, v33
	v_add_f32_e32 v32, v62, v195
	v_exp_f32_e32 v195, v34
	v_add_f32_e32 v32, v63, v32
	v_exp_f32_e32 v202, v35
	v_add_f32_e32 v32, v200, v32
	v_exp_f32_e32 v36, v36
	v_add_f32_e32 v32, v201, v32
	v_exp_f32_e32 v37, v37
	v_add_f32_e32 v32, v195, v32
	v_add_f32_e32 v32, v202, v32
	v_add_f32_e32 v32, v36, v32
	v_add_f32_e32 v203, v37, v32
	v_cvt_pk_bf16_f32 v32, v48, v49
	v_cvt_pk_bf16_f32 v33, v50, v51
	v_cvt_pk_bf16_f32 v34, v52, v53
	v_cvt_pk_bf16_f32 v35, v54, v55
	v_exp_f32_e32 v38, v38
	s_waitcnt lgkmcnt(7)
	s_setprio 2
	v_mfma_f32_32x32x16_bf16 v[16:31], v[156:159], v[32:35], v[16:31]
	s_setprio 0
	v_exp_f32_e32 v39, v39
	v_exp_f32_e32 v40, v40
	v_add_f32_e32 v48, v38, v203
	v_exp_f32_e32 v42, v42
	s_waitcnt lgkmcnt(5)
	s_setprio 2
	v_mfma_f32_32x32x16_bf16 v[0:15], v[152:155], v[32:35], v[0:15]
	s_setprio 0
	v_exp_f32_e32 v41, v41
	v_cvt_pk_bf16_f32 v32, v56, v57
	v_cvt_pk_bf16_f32 v33, v58, v59
	v_cvt_pk_bf16_f32 v34, v60, v61
	v_cvt_pk_bf16_f32 v35, v62, v63
	v_add_f32_e32 v48, v39, v48
	s_nop 0
	s_setprio 2
	v_mfma_f32_32x32x16_bf16 v[16:31], v[148:151], v[32:35], v[16:31]
	s_setprio 0
	v_exp_f32_e32 v43, v43
	v_add_f32_e32 v48, v40, v48
	v_exp_f32_e32 v44, v44
	v_add_f32_e32 v48, v41, v48
	s_waitcnt lgkmcnt(4)
	s_setprio 2
	v_mfma_f32_32x32x16_bf16 v[0:15], v[144:147], v[32:35], v[0:15]
	s_setprio 0
	v_add_f32_e32 v32, v42, v48
	v_add_f32_e32 v32, v43, v32
	v_add_f32_e32 v48, v44, v32
	v_cvt_pk_bf16_f32 v32, v200, v201
	v_cvt_pk_bf16_f32 v33, v195, v202
	v_cvt_pk_bf16_f32 v34, v36, v37
	v_cvt_pk_bf16_f32 v35, v38, v39
	v_exp_f32_e32 v36, v45
	s_waitcnt lgkmcnt(3)
	s_setprio 2
	v_mfma_f32_32x32x16_bf16 v[16:31], v[140:143], v[32:35], v[16:31]
	s_setprio 0
	v_exp_f32_e32 v37, v46
	v_exp_f32_e32 v38, v47
	v_add_f32_e32 v39, v36, v48
	s_waitcnt lgkmcnt(2)
	s_setprio 2
	v_mfma_f32_32x32x16_bf16 v[0:15], v[136:139], v[32:35], v[0:15]
	s_setprio 0
	v_add_f32_e32 v32, v37, v39
	v_add_f32_e32 v32, v38, v32
	v_add_f32_e32 v213, v213, v32
	v_cvt_pk_bf16_f32 v32, v40, v41
	v_cvt_pk_bf16_f32 v33, v42, v43
	v_cvt_pk_bf16_f32 v34, v44, v36
	v_cvt_pk_bf16_f32 v35, v37, v38
	s_waitcnt lgkmcnt(1)
	s_nop 0
	s_setprio 2
	v_mfma_f32_32x32x16_bf16 v[16:31], v[132:135], v[32:35], v[16:31]
	ds_read_b128 v[36:39], v210 offset:13312
	ds_read_b128 v[132:135], v210 offset:13344
	ds_read_b128 v[136:139], v210 offset:13376
	ds_read_b128 v[140:143], v210 offset:13408
	ds_read_b128 v[144:147], v210 offset:13440
	ds_read_b128 v[148:151], v210 offset:13472
	ds_read_b128 v[40:43], v210 offset:19968
	ds_read_b128 v[152:155], v210 offset:20000
	ds_read_b128 v[156:159], v210 offset:20032
	ds_read_b128 v[234:237], v210 offset:20064
	ds_read_b128 v[238:241], v210 offset:20096
	ds_read_b128 v[242:245], v210 offset:20128
	s_waitcnt lgkmcnt(12)
	v_mfma_f32_32x32x16_bf16 v[0:15], v[128:131], v[32:35], v[0:15]
	s_setprio 0
	s_branch .Lsc0_mj0
.Lsc0_fb1:
	ds_read_b128 v[36:39], v210 offset:13312
	ds_read_b128 v[132:135], v210 offset:13344
	ds_read_b128 v[136:139], v210 offset:13376
	ds_read_b128 v[140:143], v210 offset:13408
	ds_read_b128 v[144:147], v210 offset:13440
	ds_read_b128 v[148:151], v210 offset:13472
	ds_read_b128 v[40:43], v210 offset:19968
	ds_read_b128 v[152:155], v210 offset:20000
	ds_read_b128 v[156:159], v210 offset:20032
	ds_read_b128 v[234:237], v210 offset:20064
	ds_read_b128 v[238:241], v210 offset:20096
	ds_read_b128 v[242:245], v210 offset:20128
	s_waitcnt lgkmcnt(0)
	s_waitcnt lgkmcnt(11)
	s_setprio 2
	v_mfma_f32_32x32x16_bf16 v[48:63], v[36:39], v[64:67], v[176:191]
	s_waitcnt lgkmcnt(5)
	v_mfma_f32_32x32x16_bf16 v[32:47], v[40:43], v[64:67], v[176:191]
	v_mfma_f32_32x32x16_bf16 v[48:63], v[132:135], v[68:71], v[48:63]
	s_waitcnt lgkmcnt(4)
	v_mfma_f32_32x32x16_bf16 v[32:47], v[152:155], v[68:71], v[32:47]
	v_mfma_f32_32x32x16_bf16 v[48:63], v[136:139], v[72:75], v[48:63]
	s_waitcnt lgkmcnt(3)
	v_mfma_f32_32x32x16_bf16 v[32:47], v[156:159], v[72:75], v[32:47]
	v_mfma_f32_32x32x16_bf16 v[48:63], v[140:143], v[88:91], v[48:63]
	s_waitcnt lgkmcnt(2)
	v_mfma_f32_32x32x16_bf16 v[32:47], v[234:237], v[88:91], v[32:47]
	v_mfma_f32_32x32x16_bf16 v[48:63], v[144:147], v[96:99], v[48:63]
	s_waitcnt lgkmcnt(1)
	v_mfma_f32_32x32x16_bf16 v[32:47], v[238:241], v[96:99], v[32:47]
	v_mfma_f32_32x32x16_bf16 v[48:63], v[148:151], v[100:103], v[48:63]
	s_waitcnt lgkmcnt(0)
	v_mfma_f32_32x32x16_bf16 v[32:47], v[242:245], v[100:103], v[32:47]
	s_setprio 0
	s_nop 3
	ds_read_b128 v[156:159], v211 offset:128
	ds_read_b128 v[148:151], v211 offset:160
	ds_read_b128 v[152:155], v211 offset:8832
	ds_read_b128 v[144:147], v211 offset:8864
	ds_read_b128 v[140:143], v211 offset:192
	ds_read_b128 v[136:139], v211 offset:8896
	ds_read_b128 v[128:131], v211 offset:224
	ds_read_b128 v[132:135], v211 offset:8928
	v_max3_f32 v195, v32, v48, v49
	v_max_f32_e32 v195, v195, v33
	v_max3_f32 v195, v195, v50, v34
	v_max3_f32 v195, v195, v51, v35
	v_max3_f32 v195, v195, v52, v36
	v_max3_f32 v195, v195, v53, v37
	v_max3_f32 v195, v195, v54, v38
	v_max3_f32 v195, v195, v55, v39
	v_max3_f32 v195, v195, v56, v40
	v_max3_f32 v195, v195, v57, v41
	v_max3_f32 v195, v195, v58, v42
	v_max3_f32 v195, v195, v59, v43
	v_max3_f32 v195, v195, v60, v44
	v_max3_f32 v195, v195, v61, v45
	v_max3_f32 v195, v195, v62, v46
	v_max3_f32 v214, v195, v63, v47
	v_cmp_gt_f32_e32 vcc, v214, v220
	s_cbranch_vccz .Lsc0_c1_LBB0_801
; #define MFMA(a, b, c) __builtin_amdgcn_mfma_f32_32x32x16_bf16((a), (b), (c), 0, 0, 0)
; DI float fexp2(float x) { return __builtin_amdgcn_exp2f(x); }
; DI void phase_attn(const Params& p, int hf, bool skipctx, char* smem, int& rot) {
;     ...
;       if (__any(mx > m_run + 8.f)) {
;         mx = fmaxf(mx, __shfl_xor(mx, 32));
;         const float m_new = fmaxf(m_run, mx);
;         const float alpha = fexp2(m_run - m_new);
;         m_run = m_new;
;         l_run *= alpha;
; #pragma unroll
;         for (int i = 0; i < 16; ++i) { o[0][i] *= alpha; o[1][i] *= alpha; }
;       }
;       float ps = 0.f;
; #pragma unroll
;       for (int kb = 0; kb < 2; ++kb)
; #pragma unroll
;         for (int i = 0; i < 16; ++i) { const float e = fexp2(st[kb][i] - m_run); st[kb][i] = e; ps += e; }
;       l_run += ps;
; #pragma unroll
;       for (int kb = 0; kb < 2; ++kb)
; #pragma unroll
;         for (int s2 = 0; s2 < 2; ++s2) {
;           const bf16x8 pb = pack8(st[kb][8 * s2 + 0], st[kb][8 * s2 + 1], st[kb][8 * s2 + 2], st[kb][8 * s2 + 3], st[kb][8 * s2 + 4], st[kb][8 * s2 + 5], st[kb][8 * s2 + 6], st[kb][8 * s2 + 7]);
; #pragma unroll
;           for (int dvb = 0; dvb < 2; ++dvb) o[dvb] = MFMA(vf[kb][s2][dvb], pb, o[dvb]);
;         }
;     };
;     __syncthreads();
;     ATT_LOAD(ak0, ak1, ak2, av0, av1, 0);
;     ATT_LOAD(bk0, bk1, bk2, bv0, bv1, 1);
;     ATT_WRITE(ak0, ak1, ak2, av0, av1, 0);
;     __syncthreads();
;     for (int kt = 0; kt < nkt; kt += 2) {
;       if (kt + 2 < nkt) ATT_LOAD(ak0, ak1, ak2, av0, av1, kt + 2);
;       compute(0, 0); compute(0, 1);
;       ATT_WRITE(bk0, bk1, bk2, bv0, bv1, 1);
;       __syncthreads();
;       if (kt + 3 < nkt) ATT_LOAD(bk0, bk1, bk2, bv0, bv1, kt + 3);
	v_sub_f32_e32 v214, v214, v176
	v_cmp_lt_i32_e32 vcc, v224, v207
	s_nop 1
	v_cndmask_b32_e32 v195, v205, v224, vcc
	v_lshlrev_b32_e32 v195, 2, v195
	ds_bpermute_b32 v195, v195, v214
	s_waitcnt lgkmcnt(0)
	v_max3_f32 v195, v212, v214, v195
	v_sub_f32_e32 v200, v212, v195
	v_exp_f32_e32 v200, v200
	v_mov_b32_e32 v212, v195
	v_mul_f32_e32 v213, v213, v200
	v_pk_mul_f32 v[30:31], v[30:31], v[200:201] op_sel_hi:[1,0]
	v_pk_mul_f32 v[28:29], v[28:29], v[200:201] op_sel_hi:[1,0]
	v_pk_mul_f32 v[26:27], v[26:27], v[200:201] op_sel_hi:[1,0]
	v_pk_mul_f32 v[24:25], v[24:25], v[200:201] op_sel_hi:[1,0]
	v_pk_mul_f32 v[22:23], v[22:23], v[200:201] op_sel_hi:[1,0]
	v_pk_mul_f32 v[20:21], v[20:21], v[200:201] op_sel_hi:[1,0]
	v_pk_mul_f32 v[18:19], v[18:19], v[200:201] op_sel_hi:[1,0]
	v_pk_mul_f32 v[16:17], v[16:17], v[200:201] op_sel_hi:[1,0]
	v_pk_mul_f32 v[14:15], v[14:15], v[200:201] op_sel_hi:[1,0]
	v_pk_mul_f32 v[12:13], v[12:13], v[200:201] op_sel_hi:[1,0]
	v_pk_mul_f32 v[10:11], v[10:11], v[200:201] op_sel_hi:[1,0]
	v_pk_mul_f32 v[8:9], v[8:9], v[200:201] op_sel_hi:[1,0]
	v_pk_mul_f32 v[6:7], v[6:7], v[200:201] op_sel_hi:[1,0]
	v_pk_mul_f32 v[4:5], v[4:5], v[200:201] op_sel_hi:[1,0]
	v_pk_mul_f32 v[2:3], v[2:3], v[200:201] op_sel_hi:[1,0]
	v_pk_mul_f32 v[0:1], v[0:1], v[200:201] op_sel_hi:[1,0]
	v_add_f32_e32 v202, v195, v176
	v_sub_f32_e32 v32, v32, v202
	v_sub_f32_e32 v33, v33, v202
	v_sub_f32_e32 v34, v34, v202
	v_sub_f32_e32 v35, v35, v202
	v_sub_f32_e32 v36, v36, v202
	v_sub_f32_e32 v37, v37, v202
	v_sub_f32_e32 v38, v38, v202
	v_sub_f32_e32 v39, v39, v202
	v_sub_f32_e32 v40, v40, v202
	v_sub_f32_e32 v41, v41, v202
	v_sub_f32_e32 v42, v42, v202
	v_sub_f32_e32 v43, v43, v202
	v_sub_f32_e32 v44, v44, v202
	v_sub_f32_e32 v45, v45, v202
	v_sub_f32_e32 v46, v46, v202
	v_sub_f32_e32 v47, v47, v202
	v_sub_f32_e32 v48, v48, v202
	v_sub_f32_e32 v49, v49, v202
	v_sub_f32_e32 v50, v50, v202
	v_sub_f32_e32 v51, v51, v202
	v_sub_f32_e32 v52, v52, v202
	v_sub_f32_e32 v53, v53, v202
	v_sub_f32_e32 v54, v54, v202
	v_sub_f32_e32 v55, v55, v202
	v_sub_f32_e32 v56, v56, v202
	v_sub_f32_e32 v57, v57, v202
	v_sub_f32_e32 v58, v58, v202
	v_sub_f32_e32 v59, v59, v202
	v_sub_f32_e32 v60, v60, v202
	v_sub_f32_e32 v61, v61, v202
	v_sub_f32_e32 v62, v62, v202
	v_sub_f32_e32 v63, v63, v202
	v_sub_f32_e32 v176, 0, v195
	v_sub_f32_e32 v177, 0, v195
	v_sub_f32_e32 v178, 0, v195
	v_sub_f32_e32 v179, 0, v195
	v_sub_f32_e32 v180, 0, v195
	v_sub_f32_e32 v181, 0, v195
	v_sub_f32_e32 v182, 0, v195
	v_sub_f32_e32 v183, 0, v195
	v_sub_f32_e32 v184, 0, v195
	v_sub_f32_e32 v185, 0, v195
	v_sub_f32_e32 v186, 0, v195
	v_sub_f32_e32 v187, 0, v195
	v_sub_f32_e32 v188, 0, v195
	v_sub_f32_e32 v189, 0, v195
	v_sub_f32_e32 v190, 0, v195
	v_sub_f32_e32 v191, 0, v195
	v_mov_b32_e32 v220, 0x41000000
	v_mov_b32_e32 v167, 0x43800000
	s_mov_b32 s101, 1
.Lsc0_c1_LBB0_801:
	v_exp_f32_e32 v48, v48
	v_exp_f32_e32 v49, v49
	v_exp_f32_e32 v50, v50
	v_exp_f32_e32 v51, v51
	v_exp_f32_e32 v52, v52
	v_exp_f32_e32 v53, v53
	v_exp_f32_e32 v54, v54
	v_exp_f32_e32 v55, v55
	v_cvt_pk_bf16_f32 v214, v48, v49
	v_cvt_pk_bf16_f32 v215, v50, v51
	v_cvt_pk_bf16_f32 v216, v52, v53
	v_cvt_pk_bf16_f32 v217, v54, v55
	s_waitcnt lgkmcnt(7)
	s_nop 0
	s_setprio 2
	v_mfma_f32_32x32x16_bf16 v[16:31], v[156:159], v[214:217], v[16:31]
	s_setprio 0
	v_exp_f32_e32 v56, v56
	s_waitcnt lgkmcnt(5)
	s_setprio 2
	v_mfma_f32_32x32x16_bf16 v[0:15], v[152:155], v[214:217], v[0:15]
	s_setprio 0
	v_exp_f32_e32 v57, v57
	v_exp_f32_e32 v58, v58
	v_exp_f32_e32 v59, v59
	v_exp_f32_e32 v60, v60
	v_exp_f32_e32 v61, v61
	v_exp_f32_e32 v62, v62
	v_exp_f32_e32 v63, v63
	v_cvt_pk_bf16_f32 v152, v56, v57
	v_cvt_pk_bf16_f32 v153, v58, v59
	v_cvt_pk_bf16_f32 v154, v60, v61
	v_cvt_pk_bf16_f32 v155, v62, v63
	s_nop 1
	s_setprio 2
	v_mfma_f32_32x32x16_bf16 v[16:31], v[148:151], v[152:155], v[16:31]
	s_setprio 0
	v_exp_f32_e32 v32, v32
	s_waitcnt lgkmcnt(4)
	s_setprio 2
	v_mfma_f32_32x32x16_bf16 v[0:15], v[144:147], v[152:155], v[0:15]
	s_setprio 0
	v_exp_f32_e32 v33, v33
	v_exp_f32_e32 v34, v34
	v_exp_f32_e32 v35, v35
	v_exp_f32_e32 v36, v36
	v_exp_f32_e32 v37, v37
	v_exp_f32_e32 v38, v38
	v_exp_f32_e32 v39, v39
	v_cvt_pk_bf16_f32 v144, v32, v33
	v_cvt_pk_bf16_f32 v145, v34, v35
	v_cvt_pk_bf16_f32 v146, v36, v37
	v_cvt_pk_bf16_f32 v147, v38, v39
	s_waitcnt lgkmcnt(3)
	s_nop 0
	s_setprio 2
	v_mfma_f32_32x32x16_bf16 v[16:31], v[140:143], v[144:147], v[16:31]
	s_setprio 0
	v_exp_f32_e32 v40, v40
	s_waitcnt lgkmcnt(2)
	s_setprio 2
	v_mfma_f32_32x32x16_bf16 v[0:15], v[136:139], v[144:147], v[0:15]
	s_setprio 0
	v_exp_f32_e32 v41, v41
	v_exp_f32_e32 v42, v42
	v_exp_f32_e32 v43, v43
	v_exp_f32_e32 v44, v44
	v_exp_f32_e32 v45, v45
	v_exp_f32_e32 v46, v46
	v_exp_f32_e32 v47, v47
	v_cvt_pk_bf16_f32 v136, v40, v41
	v_cvt_pk_bf16_f32 v137, v42, v43
	v_cvt_pk_bf16_f32 v138, v44, v45
	v_cvt_pk_bf16_f32 v139, v46, v47
	s_add_i32 s4, s4, 3
	s_cmp_ge_u32 s4, s13
	s_waitcnt lgkmcnt(1)
	s_setprio 2
	v_mfma_f32_32x32x16_bf16 v[16:31], v[128:131], v[136:139], v[16:31]
	s_setprio 0
	s_waitcnt vmcnt(1)
	ds_write_b128 v194, v[112:115] offset:44032
	ds_write_b128 v204, v[108:111] offset:44032
	ds_write_b128 v206, v[116:119] offset:44032
	ds_write_b64 v208, v[120:121] offset:44032
	ds_write_b64 v208, v[122:123] offset:44048
	s_waitcnt vmcnt(0)
	ds_write_b64 v208, v[124:125] offset:52736
	ds_write_b64 v208, v[126:127] offset:52752
	s_waitcnt lgkmcnt(0)
	s_barrier
	s_setprio 2
	v_mfma_f32_32x32x16_bf16 v[0:15], v[132:135], v[136:139], v[0:15]
	s_setprio 0
	s_cbranch_scc1 .Lsc0_c1_LBB0_803
	v_add_u32_e32 v200, 0x6000, v174
	v_add_u32_e32 v201, 0x6000, v172
	v_add_u32_e32 v202, 0x6000, v170
	global_load_dwordx4 v[112:115], v200, s[94:95]
	global_load_dwordx4 v[108:111], v201, s[94:95]
	global_load_dwordx4 v[116:119], v202, s[94:95]
	global_load_dwordx4 v[120:123], v166, s[94:95]
	global_load_dwordx4 v[124:127], v168, s[94:95]

; #define MFMA(a, b, c) __builtin_amdgcn_mfma_f32_32x32x16_bf16((a), (b), (c), 0, 0, 0)
; DI float fexp2(float x) { return __builtin_amdgcn_exp2f(x); }
; DI void phase_attn(const Params& p, int hf, bool skipctx, char* smem, int& rot) {
;     ...
;         bf16x8 kf[2][6];
; #pragma unroll
;         for (int kb = 0; kb < 2; ++kb)
; #pragma unroll
;           for (int ks = 0; ks < 6; ++ks) kf[kb][ks] = *(const bf16x8*)(sk + (kb * 32 + r) * KROW + (ks * 16 + h * 8) * 2);
;         __builtin_amdgcn_sched_barrier(0);
; #pragma unroll
;         for (int ks = 0; ks < 6; ++ks)
; #pragma unroll
;           for (int kb = 0; kb < 2; ++kb) st[kb] = MFMA(kf[kb][ks], qf[ks], st[kb]);
;         __builtin_amdgcn_sched_barrier(0);
;       }
;       bf16x8 vf[2][2][2];
; #pragma unroll
;       for (int kb = 0; kb < 2; ++kb)
; #pragma unroll
;         for (int s2 = 0; s2 < 2; ++s2)
; #pragma unroll
;           for (int dvb = 0; dvb < 2; ++dvb) {
;             const char* vp = sv + (dvb * 32 + r) * VROW + (kb * 32 + 16 * s2 + 4 * h) * 2;
;             const s16x4 lo = *(const s16x4*)vp, hi = *(const s16x4*)(vp + 16);
;             vf[kb][s2][dvb] = __builtin_shufflevector(lo, hi, 0, 1, 2, 3, 4, 5, 6, 7);
;           }
;       float mx = st[0][0];
; #pragma unroll
;       for (int i = 0; i < 16; ++i) { mx = fmaxf(mx, st[0][i]); mx = fmaxf(mx, st[1][i]); }
;       if (__any(mx > m_run + 8.f)) {
;         mx = fmaxf(mx, __shfl_xor(mx, 32));
;         const float m_new = fmaxf(m_run, mx);
;         const float alpha = fexp2(m_run - m_new);
;         m_run = m_new;
;         l_run *= alpha;
; #pragma unroll
;         for (int i = 0; i < 16; ++i) { o[0][i] *= alpha; o[1][i] *= alpha; }
;       }
.Lsc0_fb2:
	ds_read_b128 v[32:35], v210 offset:44032
	ds_read_b128 v[128:131], v210 offset:44064
	ds_read_b128 v[132:135], v210 offset:44096
	ds_read_b128 v[136:139], v210 offset:44128
	ds_read_b128 v[140:143], v210 offset:44160
	ds_read_b128 v[144:147], v210 offset:44192
	ds_read_b128 v[36:39], v210 offset:50688
	ds_read_b128 v[148:151], v210 offset:50720
	ds_read_b128 v[152:155], v210 offset:50752
	ds_read_b128 v[156:159], v210 offset:50784
	ds_read_b128 v[214:217], v210 offset:50816
	ds_read_b128 v[234:237], v210 offset:50848
	s_waitcnt lgkmcnt(0)
	s_waitcnt lgkmcnt(11)
	s_setprio 2
	v_mfma_f32_32x32x16_bf16 v[48:63], v[32:35], v[64:67], v[176:191]
	s_waitcnt lgkmcnt(5)
	v_mfma_f32_32x32x16_bf16 v[32:47], v[36:39], v[64:67], v[176:191]
	v_mfma_f32_32x32x16_bf16 v[48:63], v[128:131], v[68:71], v[48:63]
	s_waitcnt lgkmcnt(4)
	v_mfma_f32_32x32x16_bf16 v[32:47], v[148:151], v[68:71], v[32:47]
	v_mfma_f32_32x32x16_bf16 v[48:63], v[132:135], v[72:75], v[48:63]
	s_waitcnt lgkmcnt(3)
	v_mfma_f32_32x32x16_bf16 v[32:47], v[152:155], v[72:75], v[32:47]
	v_mfma_f32_32x32x16_bf16 v[48:63], v[136:139], v[88:91], v[48:63]
	s_waitcnt lgkmcnt(2)
	v_mfma_f32_32x32x16_bf16 v[32:47], v[156:159], v[88:91], v[32:47]
	v_mfma_f32_32x32x16_bf16 v[48:63], v[140:143], v[96:99], v[48:63]
	s_waitcnt lgkmcnt(1)
	v_mfma_f32_32x32x16_bf16 v[32:47], v[214:217], v[96:99], v[32:47]
	v_mfma_f32_32x32x16_bf16 v[48:63], v[144:147], v[100:103], v[48:63]
	s_waitcnt lgkmcnt(0)
	v_mfma_f32_32x32x16_bf16 v[32:47], v[234:237], v[100:103], v[32:47]
	s_setprio 0
	s_nop 3
	ds_read_b128 v[152:155], v211 offset:52736
	ds_read_b128 v[156:159], v211 offset:44032
	ds_read_b128 v[148:151], v211 offset:44064
	ds_read_b128 v[144:147], v211 offset:52768
	ds_read_b128 v[140:143], v211 offset:44096
	ds_read_b128 v[136:139], v211 offset:52800
	ds_read_b128 v[132:135], v211 offset:44128
	ds_read_b128 v[128:131], v211 offset:52832
	v_max3_f32 v195, v32, v48, v49
	v_max_f32_e32 v195, v195, v33
	v_max3_f32 v195, v195, v50, v34
	v_max3_f32 v195, v195, v51, v35
	v_max3_f32 v195, v195, v52, v36
	v_max3_f32 v195, v195, v53, v37
	v_max3_f32 v195, v195, v54, v38
	v_max3_f32 v195, v195, v55, v39
	v_max3_f32 v195, v195, v56, v40
	v_max3_f32 v195, v195, v57, v41
	v_max3_f32 v195, v195, v58, v42
	v_max3_f32 v195, v195, v59, v43
	v_max3_f32 v195, v195, v60, v44
	v_max3_f32 v195, v195, v61, v45
	v_max3_f32 v195, v195, v62, v46
	v_max3_f32 v215, v195, v63, v47
	v_cmp_gt_f32_e32 vcc, v215, v220
	s_cbranch_vccz .Lsc0_c2_LBB0_805
	v_sub_f32_e32 v215, v215, v176
	v_cmp_lt_i32_e32 vcc, v224, v207
	s_nop 1
	v_cndmask_b32_e32 v195, v205, v224, vcc
	v_lshlrev_b32_e32 v195, 2, v195
	ds_bpermute_b32 v195, v195, v215
	s_waitcnt lgkmcnt(0)
	v_max3_f32 v195, v212, v215, v195
	v_sub_f32_e32 v200, v212, v195
	v_exp_f32_e32 v200, v200
	v_mov_b32_e32 v212, v195
	v_mul_f32_e32 v213, v213, v200
	v_pk_mul_f32 v[30:31], v[30:31], v[200:201] op_sel_hi:[1,0]
	v_pk_mul_f32 v[28:29], v[28:29], v[200:201] op_sel_hi:[1,0]
	v_pk_mul_f32 v[26:27], v[26:27], v[200:201] op_sel_hi:[1,0]
	v_pk_mul_f32 v[24:25], v[24:25], v[200:201] op_sel_hi:[1,0]
	v_pk_mul_f32 v[22:23], v[22:23], v[200:201] op_sel_hi:[1,0]
	v_pk_mul_f32 v[20:21], v[20:21], v[200:201] op_sel_hi:[1,0]
	v_pk_mul_f32 v[18:19], v[18:19], v[200:201] op_sel_hi:[1,0]
	v_pk_mul_f32 v[16:17], v[16:17], v[200:201] op_sel_hi:[1,0]
	v_pk_mul_f32 v[14:15], v[14:15], v[200:201] op_sel_hi:[1,0]
	v_pk_mul_f32 v[12:13], v[12:13], v[200:201] op_sel_hi:[1,0]
	v_pk_mul_f32 v[10:11], v[10:11], v[200:201] op_sel_hi:[1,0]
	v_pk_mul_f32 v[8:9], v[8:9], v[200:201] op_sel_hi:[1,0]
	v_pk_mul_f32 v[6:7], v[6:7], v[200:201] op_sel_hi:[1,0]
	v_pk_mul_f32 v[4:5], v[4:5], v[200:201] op_sel_hi:[1,0]
	v_pk_mul_f32 v[2:3], v[2:3], v[200:201] op_sel_hi:[1,0]
	v_pk_mul_f32 v[0:1], v[0:1], v[200:201] op_sel_hi:[1,0]
	v_add_f32_e32 v202, v195, v176
	v_sub_f32_e32 v32, v32, v202
	v_sub_f32_e32 v33, v33, v202
	v_sub_f32_e32 v34, v34, v202
	v_sub_f32_e32 v35, v35, v202
	v_sub_f32_e32 v36, v36, v202
	v_sub_f32_e32 v37, v37, v202
	v_sub_f32_e32 v38, v38, v202
	v_sub_f32_e32 v39, v39, v202
	v_sub_f32_e32 v40, v40, v202
	v_sub_f32_e32 v41, v41, v202
	v_sub_f32_e32 v42, v42, v202
	v_sub_f32_e32 v43, v43, v202
	v_sub_f32_e32 v44, v44, v202
	v_sub_f32_e32 v45, v45, v202
	v_sub_f32_e32 v46, v46, v202
	v_sub_f32_e32 v47, v47, v202
	v_sub_f32_e32 v48, v48, v202
	v_sub_f32_e32 v49, v49, v202
	v_sub_f32_e32 v50, v50, v202
	v_sub_f32_e32 v51, v51, v202
	v_sub_f32_e32 v52, v52, v202
	v_sub_f32_e32 v53, v53, v202
	v_sub_f32_e32 v54, v54, v202
	v_sub_f32_e32 v55, v55, v202
	v_sub_f32_e32 v56, v56, v202
	v_sub_f32_e32 v57, v57, v202
	v_sub_f32_e32 v58, v58, v202
	v_sub_f32_e32 v59, v59, v202
	v_sub_f32_e32 v60, v60, v202
	v_sub_f32_e32 v61, v61, v202
	v_sub_f32_e32 v62, v62, v202
	v_sub_f32_e32 v63, v63, v202
	v_sub_f32_e32 v176, 0, v195
	v_sub_f32_e32 v177, 0, v195
	v_sub_f32_e32 v178, 0, v195
	v_sub_f32_e32 v179, 0, v195
	v_sub_f32_e32 v180, 0, v195
	v_sub_f32_e32 v181, 0, v195
	v_sub_f32_e32 v182, 0, v195
	v_sub_f32_e32 v183, 0, v195
	v_sub_f32_e32 v184, 0, v195
	v_sub_f32_e32 v185, 0, v195
	v_sub_f32_e32 v186, 0, v195
	v_sub_f32_e32 v187, 0, v195
	v_sub_f32_e32 v188, 0, v195
	v_sub_f32_e32 v189, 0, v195
	v_sub_f32_e32 v190, 0, v195
	v_sub_f32_e32 v191, 0, v195
	v_mov_b32_e32 v220, 0x41000000
	v_mov_b32_e32 v167, 0x43800000
	s_mov_b32 s101, 1
; #define MFMA(a, b, c) __builtin_amdgcn_mfma_f32_32x32x16_bf16((a), (b), (c), 0, 0, 0)
; DI float fexp2(float x) { return __builtin_amdgcn_exp2f(x); }
; DI void phase_attn(const Params& p, int hf, bool skipctx, char* smem, int& rot) {
;     ...
;         bf16x8 kf[2][6];
; #pragma unroll
;         for (int kb = 0; kb < 2; ++kb)
; #pragma unroll
;           for (int ks = 0; ks < 6; ++ks) kf[kb][ks] = *(const bf16x8*)(sk + (kb * 32 + r) * KROW + (ks * 16 + h * 8) * 2);
;         __builtin_amdgcn_sched_barrier(0);
; #pragma unroll
;         for (int ks = 0; ks < 6; ++ks)
; #pragma unroll
;           for (int kb = 0; kb < 2; ++kb) st[kb] = MFMA(kf[kb][ks], qf[ks], st[kb]);
;         __builtin_amdgcn_sched_barrier(0);
;       }
;       bf16x8 vf[2][2][2];
; #pragma unroll
;       for (int kb = 0; kb < 2; ++kb)
; #pragma unroll
;         for (int s2 = 0; s2 < 2; ++s2)
; #pragma unroll
;           for (int dvb = 0; dvb < 2; ++dvb) {
;             const char* vp = sv + (dvb * 32 + r) * VROW + (kb * 32 + 16 * s2 + 4 * h) * 2;
;             const s16x4 lo = *(const s16x4*)vp, hi = *(const s16x4*)(vp + 16);
;             vf[kb][s2][dvb] = __builtin_shufflevector(lo, hi, 0, 1, 2, 3, 4, 5, 6, 7);
;           }
;       float mx = st[0][0];
; #pragma unroll
;       for (int i = 0; i < 16; ++i) { mx = fmaxf(mx, st[0][i]); mx = fmaxf(mx, st[1][i]); }
;     ...
;       float ps = 0.f;
; #pragma unroll
;       for (int kb = 0; kb < 2; ++kb)
; #pragma unroll
;         for (int i = 0; i < 16; ++i) { const float e = fexp2(st[kb][i] - m_run); st[kb][i] = e; ps += e; }
;       l_run += ps;
; #pragma unroll
;       for (int kb = 0; kb < 2; ++kb)
; #pragma unroll
;         for (int s2 = 0; s2 < 2; ++s2) {
;           const bf16x8 pb = pack8(st[kb][8 * s2 + 0], st[kb][8 * s2 + 1], st[kb][8 * s2 + 2], st[kb][8 * s2 + 3], st[kb][8 * s2 + 4], st[kb][8 * s2 + 5], st[kb][8 * s2 + 6], st[kb][8 * s2 + 7]);
; #pragma unroll
;           for (int dvb = 0; dvb < 2; ++dvb) o[dvb] = MFMA(vf[kb][s2][dvb], pb, o[dvb]);
;         }
.Lsc0_c2_LBB0_805:
	v_exp_f32_e32 v48, v48
	v_exp_f32_e32 v49, v49
	v_exp_f32_e32 v50, v50
	v_exp_f32_e32 v51, v51
	v_exp_f32_e32 v52, v52
	v_add_f32_e32 v195, v49, v48
	v_exp_f32_e32 v53, v53
	v_add_f32_e32 v195, v50, v195
	v_exp_f32_e32 v54, v54
	v_add_f32_e32 v195, v51, v195
	v_exp_f32_e32 v55, v55
	v_add_f32_e32 v195, v52, v195
	v_exp_f32_e32 v56, v56
	v_add_f32_e32 v195, v53, v195
	v_exp_f32_e32 v57, v57
	v_add_f32_e32 v195, v54, v195
	v_exp_f32_e32 v58, v58
	v_add_f32_e32 v195, v55, v195
	v_exp_f32_e32 v59, v59
	v_add_f32_e32 v195, v56, v195
	v_exp_f32_e32 v60, v60
	v_add_f32_e32 v195, v57, v195
	v_exp_f32_e32 v61, v61
	v_add_f32_e32 v195, v58, v195
	v_exp_f32_e32 v62, v62
	v_add_f32_e32 v195, v59, v195
	v_exp_f32_e32 v63, v63
	v_add_f32_e32 v195, v60, v195
	v_exp_f32_e32 v200, v32
	v_add_f32_e32 v195, v61, v195
	v_exp_f32_e32 v201, v33
	v_add_f32_e32 v32, v62, v195
	v_exp_f32_e32 v195, v34
	v_add_f32_e32 v32, v63, v32
	v_exp_f32_e32 v202, v35
	v_add_f32_e32 v32, v200, v32
	v_exp_f32_e32 v36, v36
	v_add_f32_e32 v32, v201, v32
	v_exp_f32_e32 v37, v37
	v_add_f32_e32 v32, v195, v32
	v_add_f32_e32 v32, v202, v32
	v_add_f32_e32 v32, v36, v32
	v_add_f32_e32 v203, v37, v32
	v_cvt_pk_bf16_f32 v32, v48, v49
	v_cvt_pk_bf16_f32 v33, v50, v51
	v_cvt_pk_bf16_f32 v34, v52, v53
	v_cvt_pk_bf16_f32 v35, v54, v55
	v_exp_f32_e32 v38, v38
	s_waitcnt lgkmcnt(6)
	s_setprio 2
	v_mfma_f32_32x32x16_bf16 v[16:31], v[156:159], v[32:35], v[16:31]
	s_setprio 0
	v_exp_f32_e32 v39, v39
	v_exp_f32_e32 v40, v40
	v_add_f32_e32 v48, v38, v203
	v_exp_f32_e32 v42, v42
	s_setprio 2
	v_mfma_f32_32x32x16_bf16 v[0:15], v[152:155], v[32:35], v[0:15]
	s_setprio 0
	v_exp_f32_e32 v41, v41
	v_cvt_pk_bf16_f32 v32, v56, v57
	v_cvt_pk_bf16_f32 v33, v58, v59
	v_cvt_pk_bf16_f32 v34, v60, v61
	v_cvt_pk_bf16_f32 v35, v62, v63
	v_add_f32_e32 v48, v39, v48
	s_waitcnt lgkmcnt(5)
	s_setprio 2
	v_mfma_f32_32x32x16_bf16 v[16:31], v[148:151], v[32:35], v[16:31]
	s_setprio 0
	v_exp_f32_e32 v43, v43
	v_add_f32_e32 v48, v40, v48
	v_exp_f32_e32 v44, v44
	v_add_f32_e32 v48, v41, v48
	s_waitcnt lgkmcnt(4)
	s_setprio 2
	v_mfma_f32_32x32x16_bf16 v[0:15], v[144:147], v[32:35], v[0:15]
	s_setprio 0
	v_add_f32_e32 v32, v42, v48
	v_add_f32_e32 v32, v43, v32
	v_add_f32_e32 v48, v44, v32
	v_cvt_pk_bf16_f32 v32, v200, v201
	v_cvt_pk_bf16_f32 v33, v195, v202
	v_cvt_pk_bf16_f32 v34, v36, v37
	v_cvt_pk_bf16_f32 v35, v38, v39
	v_exp_f32_e32 v36, v45
	s_waitcnt lgkmcnt(3)
	s_setprio 2
	v_mfma_f32_32x32x16_bf16 v[16:31], v[140:143], v[32:35], v[16:31]
	s_setprio 0
	v_exp_f32_e32 v37, v46
	v_exp_f32_e32 v38, v47
	v_add_f32_e32 v39, v36, v48
	s_waitcnt lgkmcnt(2)
	s_setprio 2
	v_mfma_f32_32x32x16_bf16 v[0:15], v[136:139], v[32:35], v[0:15]
	s_setprio 0
	v_add_f32_e32 v32, v37, v39
	v_add_f32_e32 v32, v38, v32
	v_add_f32_e32 v213, v213, v32
	v_cvt_pk_bf16_f32 v32, v40, v41
	v_cvt_pk_bf16_f32 v33, v42, v43
	v_cvt_pk_bf16_f32 v34, v44, v36
	v_cvt_pk_bf16_f32 v35, v37, v38
	s_waitcnt lgkmcnt(1)
	s_nop 0
	s_setprio 2
	v_mfma_f32_32x32x16_bf16 v[16:31], v[132:135], v[32:35], v[16:31]
	ds_read_b128 v[36:39], v210 offset:57344
	ds_read_b128 v[132:135], v210 offset:57376
	ds_read_b128 v[136:139], v210 offset:57408
	ds_read_b128 v[140:143], v210 offset:57440
	ds_read_b128 v[144:147], v210 offset:57472
	ds_read_b128 v[148:151], v210 offset:57504
	ds_read_b128 v[40:43], v210 offset:64000
	ds_read_b128 v[152:155], v210 offset:64032
	ds_read_b128 v[156:159], v210 offset:64064
	ds_read_b128 v[216:219], v210 offset:64096
	ds_read_b128 v[234:237], v210 offset:64128
	ds_read_b128 v[238:241], v210 offset:64160
	s_waitcnt lgkmcnt(12)
	v_mfma_f32_32x32x16_bf16 v[0:15], v[128:131], v[32:35], v[0:15]
	s_setprio 0
	s_branch .Lsc0_mj2
.Lsc0_fb3:
	ds_read_b128 v[36:39], v210 offset:57344
	ds_read_b128 v[132:135], v210 offset:57376
	ds_read_b128 v[136:139], v210 offset:57408
	ds_read_b128 v[140:143], v210 offset:57440
	ds_read_b128 v[144:147], v210 offset:57472
	ds_read_b128 v[148:151], v210 offset:57504
	ds_read_b128 v[40:43], v210 offset:64000
	ds_read_b128 v[152:155], v210 offset:64032
	ds_read_b128 v[156:159], v210 offset:64064
	ds_read_b128 v[216:219], v210 offset:64096
	ds_read_b128 v[234:237], v210 offset:64128
	ds_read_b128 v[238:241], v210 offset:64160
	s_waitcnt lgkmcnt(0)
	s_waitcnt lgkmcnt(11)
	s_setprio 2
	v_mfma_f32_32x32x16_bf16 v[48:63], v[36:39], v[64:67], v[176:191]
	s_waitcnt lgkmcnt(5)
	v_mfma_f32_32x32x16_bf16 v[32:47], v[40:43], v[64:67], v[176:191]
	v_mfma_f32_32x32x16_bf16 v[48:63], v[132:135], v[68:71], v[48:63]
	s_waitcnt lgkmcnt(4)
	v_mfma_f32_32x32x16_bf16 v[32:47], v[152:155], v[68:71], v[32:47]
	v_mfma_f32_32x32x16_bf16 v[48:63], v[136:139], v[72:75], v[48:63]
	s_waitcnt lgkmcnt(3)
	v_mfma_f32_32x32x16_bf16 v[32:47], v[156:159], v[72:75], v[32:47]
	v_mfma_f32_32x32x16_bf16 v[48:63], v[140:143], v[88:91], v[48:63]
	s_waitcnt lgkmcnt(2)
	v_mfma_f32_32x32x16_bf16 v[32:47], v[216:219], v[88:91], v[32:47]
	v_mfma_f32_32x32x16_bf16 v[48:63], v[144:147], v[96:99], v[48:63]
	s_waitcnt lgkmcnt(1)
	v_mfma_f32_32x32x16_bf16 v[32:47], v[234:237], v[96:99], v[32:47]
	v_mfma_f32_32x32x16_bf16 v[48:63], v[148:151], v[100:103], v[48:63]
	s_waitcnt lgkmcnt(0)
	v_mfma_f32_32x32x16_bf16 v[32:47], v[238:241], v[100:103], v[32:47]
	s_setprio 0
	s_nop 3
	ds_read_b128 v[152:155], v211 offset:52864
	ds_read_b128 v[156:159], v211 offset:44160
	ds_read_b128 v[148:151], v211 offset:44192
	ds_read_b128 v[144:147], v211 offset:52896
	ds_read_b128 v[140:143], v211 offset:44224
	ds_read_b128 v[136:139], v211 offset:52928
	ds_read_b128 v[132:135], v211 offset:44256
	ds_read_b128 v[128:131], v211 offset:52960
	v_max3_f32 v195, v32, v48, v49
	v_max_f32_e32 v195, v195, v33
	v_max3_f32 v195, v195, v50, v34
	v_max3_f32 v195, v195, v51, v35
	v_max3_f32 v195, v195, v52, v36
	v_max3_f32 v195, v195, v53, v37
	v_max3_f32 v195, v195, v54, v38
	v_max3_f32 v195, v195, v55, v39
	v_max3_f32 v195, v195, v56, v40
	v_max3_f32 v195, v195, v57, v41
	v_max3_f32 v195, v195, v58, v42
	v_max3_f32 v195, v195, v59, v43
	v_max3_f32 v195, v195, v60, v44
	v_max3_f32 v195, v195, v61, v45
	v_max3_f32 v195, v195, v62, v46
	v_max3_f32 v215, v195, v63, v47
	v_cmp_gt_f32_e32 vcc, v215, v220
	s_cbranch_vccz .Lsc0_c3_LBB0_807
; #define MFMA(a, b, c) __builtin_amdgcn_mfma_f32_32x32x16_bf16((a), (b), (c), 0, 0, 0)
; DI float fexp2(float x) { return __builtin_amdgcn_exp2f(x); }
; DI void phase_attn(const Params& p, int hf, bool skipctx, char* smem, int& rot) {
;     ...
;       if (__any(mx > m_run + 8.f)) {
;         mx = fmaxf(mx, __shfl_xor(mx, 32));
;         const float m_new = fmaxf(m_run, mx);
;         const float alpha = fexp2(m_run - m_new);
;         m_run = m_new;
;         l_run *= alpha;
; #pragma unroll
;         for (int i = 0; i < 16; ++i) { o[0][i] *= alpha; o[1][i] *= alpha; }
;       }
;       float ps = 0.f;
; #pragma unroll
;       for (int kb = 0; kb < 2; ++kb)
; #pragma unroll
;         for (int i = 0; i < 16; ++i) { const float e = fexp2(st[kb][i] - m_run); st[kb][i] = e; ps += e; }
;       l_run += ps;
; #pragma unroll
;       for (int kb = 0; kb < 2; ++kb)
; #pragma unroll
;         for (int s2 = 0; s2 < 2; ++s2) {
;           const bf16x8 pb = pack8(st[kb][8 * s2 + 0], st[kb][8 * s2 + 1], st[kb][8 * s2 + 2], st[kb][8 * s2 + 3], st[kb][8 * s2 + 4], st[kb][8 * s2 + 5], st[kb][8 * s2 + 6], st[kb][8 * s2 + 7]);
; #pragma unroll
;           for (int dvb = 0; dvb < 2; ++dvb) o[dvb] = MFMA(vf[kb][s2][dvb], pb, o[dvb]);
;         }
	v_sub_f32_e32 v215, v215, v176
	v_cmp_lt_i32_e32 vcc, v224, v207
	s_nop 1
	v_cndmask_b32_e32 v195, v205, v224, vcc
	v_lshlrev_b32_e32 v195, 2, v195
	ds_bpermute_b32 v195, v195, v215
	s_waitcnt lgkmcnt(0)
	v_max3_f32 v195, v212, v215, v195
	v_sub_f32_e32 v200, v212, v195
	v_exp_f32_e32 v200, v200
	v_mov_b32_e32 v212, v195
	v_mul_f32_e32 v213, v213, v200
	v_pk_mul_f32 v[30:31], v[30:31], v[200:201] op_sel_hi:[1,0]
	v_pk_mul_f32 v[28:29], v[28:29], v[200:201] op_sel_hi:[1,0]
	v_pk_mul_f32 v[26:27], v[26:27], v[200:201] op_sel_hi:[1,0]
	v_pk_mul_f32 v[24:25], v[24:25], v[200:201] op_sel_hi:[1,0]
	v_pk_mul_f32 v[22:23], v[22:23], v[200:201] op_sel_hi:[1,0]
	v_pk_mul_f32 v[20:21], v[20:21], v[200:201] op_sel_hi:[1,0]
	v_pk_mul_f32 v[18:19], v[18:19], v[200:201] op_sel_hi:[1,0]
	v_pk_mul_f32 v[16:17], v[16:17], v[200:201] op_sel_hi:[1,0]
	v_pk_mul_f32 v[14:15], v[14:15], v[200:201] op_sel_hi:[1,0]
	v_pk_mul_f32 v[12:13], v[12:13], v[200:201] op_sel_hi:[1,0]
	v_pk_mul_f32 v[10:11], v[10:11], v[200:201] op_sel_hi:[1,0]
	v_pk_mul_f32 v[8:9], v[8:9], v[200:201] op_sel_hi:[1,0]
	v_pk_mul_f32 v[6:7], v[6:7], v[200:201] op_sel_hi:[1,0]
	v_pk_mul_f32 v[4:5], v[4:5], v[200:201] op_sel_hi:[1,0]
	v_pk_mul_f32 v[2:3], v[2:3], v[200:201] op_sel_hi:[1,0]
	v_pk_mul_f32 v[0:1], v[0:1], v[200:201] op_sel_hi:[1,0]
	v_add_f32_e32 v202, v195, v176
	v_sub_f32_e32 v32, v32, v202
	v_sub_f32_e32 v33, v33, v202
	v_sub_f32_e32 v34, v34, v202
	v_sub_f32_e32 v35, v35, v202
	v_sub_f32_e32 v36, v36, v202
	v_sub_f32_e32 v37, v37, v202
	v_sub_f32_e32 v38, v38, v202
	v_sub_f32_e32 v39, v39, v202
	v_sub_f32_e32 v40, v40, v202
	v_sub_f32_e32 v41, v41, v202
	v_sub_f32_e32 v42, v42, v202
	v_sub_f32_e32 v43, v43, v202
	v_sub_f32_e32 v44, v44, v202
	v_sub_f32_e32 v45, v45, v202
	v_sub_f32_e32 v46, v46, v202
	v_sub_f32_e32 v47, v47, v202
	v_sub_f32_e32 v48, v48, v202
	v_sub_f32_e32 v49, v49, v202
	v_sub_f32_e32 v50, v50, v202
	v_sub_f32_e32 v51, v51, v202
	v_sub_f32_e32 v52, v52, v202
	v_sub_f32_e32 v53, v53, v202
	v_sub_f32_e32 v54, v54, v202
	v_sub_f32_e32 v55, v55, v202
	v_sub_f32_e32 v56, v56, v202
	v_sub_f32_e32 v57, v57, v202
	v_sub_f32_e32 v58, v58, v202
	v_sub_f32_e32 v59, v59, v202
	v_sub_f32_e32 v60, v60, v202
	v_sub_f32_e32 v61, v61, v202
	v_sub_f32_e32 v62, v62, v202
	v_sub_f32_e32 v63, v63, v202
	v_sub_f32_e32 v176, 0, v195
	v_sub_f32_e32 v177, 0, v195
	v_sub_f32_e32 v178, 0, v195
	v_sub_f32_e32 v179, 0, v195
	v_sub_f32_e32 v180, 0, v195
	v_sub_f32_e32 v181, 0, v195
	v_sub_f32_e32 v182, 0, v195
	v_sub_f32_e32 v183, 0, v195
	v_sub_f32_e32 v184, 0, v195
	v_sub_f32_e32 v185, 0, v195
	v_sub_f32_e32 v186, 0, v195
	v_sub_f32_e32 v187, 0, v195
	v_sub_f32_e32 v188, 0, v195
	v_sub_f32_e32 v189, 0, v195
	v_sub_f32_e32 v190, 0, v195
	v_sub_f32_e32 v191, 0, v195
	v_mov_b32_e32 v220, 0x41000000
	v_mov_b32_e32 v167, 0x43800000
	s_mov_b32 s101, 1
.Lsc0_c3_LBB0_807:
	v_exp_f32_e32 v48, v48
	v_exp_f32_e32 v49, v49
	v_exp_f32_e32 v50, v50
	v_exp_f32_e32 v51, v51
	v_exp_f32_e32 v52, v52
	v_exp_f32_e32 v53, v53
	v_exp_f32_e32 v54, v54
	v_exp_f32_e32 v55, v55
	v_cvt_pk_bf16_f32 v214, v48, v49
	v_cvt_pk_bf16_f32 v215, v50, v51
	v_cvt_pk_bf16_f32 v216, v52, v53
	v_cvt_pk_bf16_f32 v217, v54, v55
	s_waitcnt lgkmcnt(6)
	s_nop 0
	s_setprio 2
	v_mfma_f32_32x32x16_bf16 v[16:31], v[156:159], v[214:217], v[16:31]
	s_setprio 0
	v_exp_f32_e32 v56, v56
	s_setprio 2
	v_mfma_f32_32x32x16_bf16 v[0:15], v[152:155], v[214:217], v[0:15]
	s_setprio 0
	v_exp_f32_e32 v57, v57
	v_exp_f32_e32 v58, v58
	v_exp_f32_e32 v59, v59
	v_exp_f32_e32 v60, v60
	v_exp_f32_e32 v61, v61
	v_exp_f32_e32 v62, v62
	v_exp_f32_e32 v63, v63
	v_cvt_pk_bf16_f32 v152, v56, v57
	v_cvt_pk_bf16_f32 v153, v58, v59
	v_cvt_pk_bf16_f32 v154, v60, v61
	v_cvt_pk_bf16_f32 v155, v62, v63
	s_waitcnt lgkmcnt(5)
	s_nop 0
	s_setprio 2
	v_mfma_f32_32x32x16_bf16 v[16:31], v[148:151], v[152:155], v[16:31]
	s_setprio 0
	v_exp_f32_e32 v32, v32
	s_waitcnt lgkmcnt(4)
	s_setprio 2
	v_mfma_f32_32x32x16_bf16 v[0:15], v[144:147], v[152:155], v[0:15]
	s_setprio 0
	v_exp_f32_e32 v33, v33
	v_exp_f32_e32 v34, v34
	v_exp_f32_e32 v35, v35
	v_exp_f32_e32 v36, v36
	v_exp_f32_e32 v37, v37
	v_exp_f32_e32 v38, v38
	v_exp_f32_e32 v39, v39
	v_cvt_pk_bf16_f32 v144, v32, v33
	v_cvt_pk_bf16_f32 v145, v34, v35
	v_cvt_pk_bf16_f32 v146, v36, v37
	v_cvt_pk_bf16_f32 v147, v38, v39
	s_waitcnt lgkmcnt(3)
	s_nop 0
	s_setprio 2
	v_mfma_f32_32x32x16_bf16 v[16:31], v[140:143], v[144:147], v[16:31]
	s_setprio 0
	v_exp_f32_e32 v40, v40
	s_waitcnt lgkmcnt(2)
	s_setprio 2
	v_mfma_f32_32x32x16_bf16 v[0:15], v[136:139], v[144:147], v[0:15]
	s_setprio 0
	v_exp_f32_e32 v41, v41
	v_exp_f32_e32 v42, v42
	v_exp_f32_e32 v43, v43
	v_exp_f32_e32 v44, v44
	v_exp_f32_e32 v45, v45
	v_exp_f32_e32 v46, v46
	v_exp_f32_e32 v47, v47
	v_cvt_pk_bf16_f32 v136, v40, v41
	v_cvt_pk_bf16_f32 v137, v42, v43
	v_cvt_pk_bf16_f32 v138, v44, v45
	v_cvt_pk_bf16_f32 v139, v46, v47
	s_andn2_b64 vcc, exec, s[36:37]
	s_waitcnt lgkmcnt(1)
	s_setprio 2
	v_mfma_f32_32x32x16_bf16 v[16:31], v[132:135], v[136:139], v[16:31]
	s_waitcnt lgkmcnt(0)
	v_mfma_f32_32x32x16_bf16 v[0:15], v[128:131], v[136:139], v[0:15]
	s_setprio 0
	s_cbranch_vccnz .Lsc0_c3_LBB0_809
	ds_write_b128 v194, v[76:79]
	ds_write_b128 v204, v[80:83]
	ds_write_b128 v206, v[84:87]
	ds_write_b64 v208, v[92:93] offset:0
	ds_write_b64 v208, v[94:95] offset:16
	ds_write_b64 v208, v[104:105] offset:8704
	ds_write_b64 v208, v[106:107] offset:8720
